# GEMM K-loops: first 4 MFMAs of every MMA segment issued before the segment's barrier (operands already in registers) to keep the matrix pipe fed across the half-workgroup hand-off
# speedup vs baseline: 1.0112x; 1.0006x over previous
; #define PG8_STAGE(bufoff, gbase, voff) do { _Pragma("unroll") for (int _i = 0; _i < 2; ++_i) \
;         __builtin_amdgcn_global_load_lds((const unsigned*)((const char*)(gbase) + (voff)[_i]), (PG8_LAS unsigned*)(lds + (bufoff) + ldsw + _i * 8192), 16, 0, 0); } while (0)
; #define PG8_LDA(dst, b, h) do { _Pragma("unroll") for (int m = 0; m < 4; ++m) _Pragma("unroll") for (int k = 0; k < 2; ++k) dst[m][k] = *(const PG8_LAS bf16x8*)(lds + PG8_SA(b, h) + aoff + m * 2048 + k * 1024); } while (0)
; #define PG8_LDB(dst, b, h) do { _Pragma("unroll") for (int n = 0; n < 2; ++n) _Pragma("unroll") for (int k = 0; k < 2; ++k) dst[n][k] = *(const PG8_LAS bf16x8*)(lds + PG8_SB(b, h) + boff + n * 2048 + k * 1024); } while (0)
; #define PG8_MMA(ai, bj, At, Bt) do { __builtin_amdgcn_s_setprio(1); _Pragma("unroll") for (int m = 0; m < 4; ++m) _Pragma("unroll") for (int n = 0; n < 2; ++n) _Pragma("unroll") for (int k = 0; k < 2; ++k) \
;         acc[ai][bj][m][n] = __builtin_amdgcn_mfma_f32_16x16x32_bf16(Bt[n][k], At[m][k], acc[ai][bj][m][n], 0, 0, 0); __builtin_amdgcn_s_setprio(0); } while (0)
; #define PG8_BAR __builtin_amdgcn_s_barrier()
; template <class Epi, class Sched, bool ALIGN_EPI = false, bool SP2 = false>
; __device__ __forceinline__ void gemm_phase(PG8_LAS unsigned char* lds, const Gemm g, const Sched& S, const Epi& E) {
;     ...
;             if constexpr (SP2) {
;             PG8_LDB(B0, 0, 0); PG8_LDB(B1, 0, 1); PG8_SCHED; PG8_LDA(At, 0, 0); PG8_STAGE(PG8_SA(1, 1), a1 + hstep, voffA);
;             PG8_WAIT_V(8); PG8_WAIT_L(0); PG8_BAR; PG8_MMA(0, 0, At, B0); PG8_MMA(0, 1, At, B1); PG8_BAR; PG8_SCHED;
;             PG8_LDA(At, 0, 1); PG8_STAGE(PG8_SB(0, 0), b2, voffB); PG8_STAGE(PG8_SB(0, 1), b2 + hstep, voffB); PG8_STAGE(PG8_SA(0, 0), a2, voffA);
;             PG8_WAIT_V(8); PG8_WAIT_L(0); PG8_BAR; PG8_MMA(1, 0, At, B0); PG8_MMA(1, 1, At, B1); PG8_BAR; PG8_SCHED;
;             PG8_LDB(B0, 1, 0); PG8_LDB(B1, 1, 1); PG8_SCHED; PG8_LDA(At, 1, 0); PG8_STAGE(PG8_SA(0, 1), a2 + hstep, voffA);
;             PG8_WAIT_V(8); PG8_WAIT_L(0); PG8_BAR; PG8_MMA(0, 0, At, B0); PG8_MMA(0, 1, At, B1); PG8_BAR; PG8_SCHED;
;             PG8_LDA(At, 1, 1); PG8_STAGE(PG8_SB(1, 0), b3, voffB); PG8_STAGE(PG8_SB(1, 1), b3 + hstep, voffB); PG8_STAGE(PG8_SA(1, 0), a3, voffA);
;             PG8_WAIT_V(8); PG8_WAIT_L(0); PG8_BAR; PG8_MMA(1, 0, At, B0); PG8_MMA(1, 1, At, B1); PG8_BAR; PG8_SCHED;
.LBB0_102:
	ds_read_b128 v[146:149], v152
	ds_read_b128 v[156:159], v152 offset:1024
	ds_read_b128 v[160:163], v152 offset:2048
	ds_read_b128 v[164:167], v152 offset:3072
	ds_read_b128 v[172:175], v153
	ds_read_b128 v[176:179], v153 offset:1024
	ds_read_b128 v[180:183], v153 offset:2048
	ds_read_b128 v[184:187], v153 offset:3072
	s_add_u32 s2, s28, 0xfffc0080
	s_addc_u32 s3, s29, -1
	s_cmp_eq_u32 s46, 12
	s_cselect_b32 s17, s19, s3
	s_cselect_b32 s16, s44, s2
	s_cselect_b32 s3, s15, s31
	s_cselect_b32 s2, s45, s30
	v_lshl_add_u64 v[222:223], s[28:29], 0, v[138:139]
	s_add_i32 m0, s25, 0xc000
	ds_read_b128 v[188:191], v154
	ds_read_b128 v[192:195], v154 offset:1024
	ds_read_b128 v[198:201], v154 offset:2048
	ds_read_b128 v[202:205], v154 offset:3072
	ds_read_b128 v[206:209], v154 offset:4096
	ds_read_b128 v[210:213], v154 offset:5120
	ds_read_b128 v[214:217], v154 offset:6144
	ds_read_b128 v[218:221], v154 offset:7168
	global_load_lds_dwordx4 v[222:223], off
	v_lshl_add_u64 v[222:223], s[28:29], 0, v[140:141]
	s_add_i32 m0, s25, 0xe000
	s_nop 0
	global_load_lds_dwordx4 v[222:223], off
	s_waitcnt vmcnt(8)
	s_waitcnt lgkmcnt(0)
	v_mfma_f32_16x16x32_bf16 v[126:129], v[146:149], v[188:191], v[126:129]
	v_mfma_f32_16x16x32_bf16 v[118:121], v[160:163], v[188:191], v[118:121]
	v_mfma_f32_16x16x32_bf16 v[110:113], v[146:149], v[198:201], v[110:113]
	v_mfma_f32_16x16x32_bf16 v[102:105], v[160:163], v[198:201], v[102:105]
	s_barrier
	s_setprio 1
	s_waitcnt lgkmcnt(0)
	v_mfma_f32_16x16x32_bf16 v[94:97], v[146:149], v[206:209], v[94:97]
	v_mfma_f32_16x16x32_bf16 v[86:89], v[160:163], v[206:209], v[86:89]
	v_mfma_f32_16x16x32_bf16 v[78:81], v[146:149], v[214:217], v[78:81]
	v_mfma_f32_16x16x32_bf16 v[70:73], v[160:163], v[214:217], v[70:73]
	v_mfma_f32_16x16x32_bf16 v[126:129], v[156:159], v[192:195], v[126:129]
	v_mfma_f32_16x16x32_bf16 v[118:121], v[164:167], v[192:195], v[118:121]
	v_mfma_f32_16x16x32_bf16 v[110:113], v[156:159], v[202:205], v[110:113]
	v_mfma_f32_16x16x32_bf16 v[102:105], v[164:167], v[202:205], v[102:105]
	v_mfma_f32_16x16x32_bf16 v[94:97], v[156:159], v[210:213], v[94:97]
	v_mfma_f32_16x16x32_bf16 v[86:89], v[164:167], v[210:213], v[86:89]
	v_mfma_f32_16x16x32_bf16 v[78:81], v[156:159], v[218:221], v[78:81]
	v_mfma_f32_16x16x32_bf16 v[70:73], v[164:167], v[218:221], v[70:73]
	s_setprio 0
	s_setprio 1
	v_mfma_f32_16x16x32_bf16 v[122:125], v[172:175], v[188:191], v[122:125]
	v_mfma_f32_16x16x32_bf16 v[114:117], v[180:183], v[188:191], v[114:117]
	v_mfma_f32_16x16x32_bf16 v[106:109], v[172:175], v[198:201], v[106:109]
	v_mfma_f32_16x16x32_bf16 v[98:101], v[180:183], v[198:201], v[98:101]
	v_mfma_f32_16x16x32_bf16 v[90:93], v[172:175], v[206:209], v[90:93]
	v_mfma_f32_16x16x32_bf16 v[82:85], v[180:183], v[206:209], v[82:85]
	v_mfma_f32_16x16x32_bf16 v[74:77], v[172:175], v[214:217], v[74:77]
	v_mfma_f32_16x16x32_bf16 v[66:69], v[180:183], v[214:217], v[66:69]
	v_mfma_f32_16x16x32_bf16 v[122:125], v[176:179], v[192:195], v[122:125]
	v_mfma_f32_16x16x32_bf16 v[114:117], v[184:187], v[192:195], v[114:117]
	v_mfma_f32_16x16x32_bf16 v[106:109], v[176:179], v[202:205], v[106:109]
	v_mfma_f32_16x16x32_bf16 v[98:101], v[184:187], v[202:205], v[98:101]
	v_mfma_f32_16x16x32_bf16 v[90:93], v[176:179], v[210:213], v[90:93]
	v_mfma_f32_16x16x32_bf16 v[82:85], v[184:187], v[210:213], v[82:85]
	v_mfma_f32_16x16x32_bf16 v[74:77], v[176:179], v[218:221], v[74:77]
	v_mfma_f32_16x16x32_bf16 v[66:69], v[184:187], v[218:221], v[66:69]
	s_setprio 0
	s_barrier
	s_add_i32 s47, s40, s27
	v_lshl_add_u64 v[222:223], s[2:3], 0, v[132:133]
	s_mov_b32 m0, s47
	ds_read_b128 v[188:191], v154 offset:16384
	ds_read_b128 v[192:195], v154 offset:17408
	ds_read_b128 v[198:201], v154 offset:18432
	ds_read_b128 v[202:205], v154 offset:19456
	ds_read_b128 v[206:209], v154 offset:20480
	ds_read_b128 v[210:213], v154 offset:21504
	ds_read_b128 v[214:217], v154 offset:22528
	ds_read_b128 v[218:221], v154 offset:23552
	global_load_lds_dwordx4 v[222:223], off
	s_add_i32 m0, s47, 0x2000
	s_add_u32 s48, s2, 0x40000
	v_lshl_add_u64 v[224:225], s[2:3], 0, v[136:137]
	s_addc_u32 s49, s3, 0
	s_add_i32 s47, s41, s27
	global_load_lds_dwordx4 v[224:225], off
	v_lshl_add_u64 v[226:227], s[48:49], 0, v[132:133]
	s_mov_b32 m0, s47
	v_lshl_add_u64 v[228:229], s[16:17], 0, v[134:135]
	global_load_lds_dwordx4 v[226:227], off
	v_lshl_add_u64 v[226:227], s[48:49], 0, v[136:137]
	s_add_i32 m0, s47, 0x2000
	s_nop 0
	global_load_lds_dwordx4 v[226:227], off
	v_lshl_add_u64 v[226:227], s[16:17], 0, v[130:131]
	s_mov_b32 m0, s25
	s_nop 0
	global_load_lds_dwordx4 v[226:227], off
	s_mov_b32 m0, s33
	s_nop 0
	global_load_lds_dwordx4 v[228:229], off
	s_waitcnt vmcnt(8)
	s_waitcnt lgkmcnt(0)
	v_mfma_f32_16x16x32_bf16 v[62:65], v[146:149], v[188:191], v[62:65]
	v_mfma_f32_16x16x32_bf16 v[54:57], v[160:163], v[188:191], v[54:57]
	v_mfma_f32_16x16x32_bf16 v[46:49], v[146:149], v[198:201], v[46:49]
	v_mfma_f32_16x16x32_bf16 v[38:41], v[160:163], v[198:201], v[38:41]
	s_barrier
; #define PG8_STAGE(bufoff, gbase, voff) do { _Pragma("unroll") for (int _i = 0; _i < 2; ++_i) \
;         __builtin_amdgcn_global_load_lds((const unsigned*)((const char*)(gbase) + (voff)[_i]), (PG8_LAS unsigned*)(lds + (bufoff) + ldsw + _i * 8192), 16, 0, 0); } while (0)
; #define PG8_LDA(dst, b, h) do { _Pragma("unroll") for (int m = 0; m < 4; ++m) _Pragma("unroll") for (int k = 0; k < 2; ++k) dst[m][k] = *(const PG8_LAS bf16x8*)(lds + PG8_SA(b, h) + aoff + m * 2048 + k * 1024); } while (0)
; #define PG8_LDB(dst, b, h) do { _Pragma("unroll") for (int n = 0; n < 2; ++n) _Pragma("unroll") for (int k = 0; k < 2; ++k) dst[n][k] = *(const PG8_LAS bf16x8*)(lds + PG8_SB(b, h) + boff + n * 2048 + k * 1024); } while (0)
; #define PG8_MMA(ai, bj, At, Bt) do { __builtin_amdgcn_s_setprio(1); _Pragma("unroll") for (int m = 0; m < 4; ++m) _Pragma("unroll") for (int n = 0; n < 2; ++n) _Pragma("unroll") for (int k = 0; k < 2; ++k) \
;         acc[ai][bj][m][n] = __builtin_amdgcn_mfma_f32_16x16x32_bf16(Bt[n][k], At[m][k], acc[ai][bj][m][n], 0, 0, 0); __builtin_amdgcn_s_setprio(0); } while (0)
; #define PG8_WAIT_V(n) asm volatile("s_waitcnt vmcnt(" #n ")" ::: "memory")
; #define PG8_WAIT_L(n) asm volatile("s_waitcnt lgkmcnt(" #n ")" ::: "memory")
; #define PG8_BAR __builtin_amdgcn_s_barrier()
; #define PG8_SCHED __builtin_amdgcn_sched_barrier(0)
; template <class Epi, class Sched, bool ALIGN_EPI = false, bool SP2 = false>
; __device__ __forceinline__ void gemm_phase(PG8_LAS unsigned char* lds, const Gemm g, const Sched& S, const Epi& E) {
;     ...
;             PG8_WAIT_V(8); PG8_WAIT_L(0); PG8_BAR; PG8_MMA(0, 0, At, B0); PG8_MMA(0, 1, At, B1); PG8_BAR; PG8_SCHED;
;             PG8_LDA(At, 0, 1); PG8_STAGE(PG8_SB(0, 0), b2, voffB); PG8_STAGE(PG8_SB(0, 1), b2 + hstep, voffB); PG8_STAGE(PG8_SA(0, 0), a2, voffA);
;             PG8_WAIT_V(8); PG8_WAIT_L(0); PG8_BAR; PG8_MMA(1, 0, At, B0); PG8_MMA(1, 1, At, B1); PG8_BAR; PG8_SCHED;
;             PG8_LDB(B0, 1, 0); PG8_LDB(B1, 1, 1); PG8_SCHED; PG8_LDA(At, 1, 0); PG8_STAGE(PG8_SA(0, 1), a2 + hstep, voffA);
;             PG8_WAIT_V(8); PG8_WAIT_L(0); PG8_BAR; PG8_MMA(0, 0, At, B0); PG8_MMA(0, 1, At, B1); PG8_BAR; PG8_SCHED;
	s_setprio 1
	s_waitcnt lgkmcnt(0)
	v_mfma_f32_16x16x32_bf16 v[30:33], v[146:149], v[206:209], v[30:33]
	v_mfma_f32_16x16x32_bf16 v[22:25], v[160:163], v[206:209], v[22:25]
	v_mfma_f32_16x16x32_bf16 v[14:17], v[146:149], v[214:217], v[14:17]
	v_mfma_f32_16x16x32_bf16 v[6:9], v[160:163], v[214:217], v[6:9]
	v_mfma_f32_16x16x32_bf16 v[62:65], v[156:159], v[192:195], v[62:65]
	v_mfma_f32_16x16x32_bf16 v[54:57], v[164:167], v[192:195], v[54:57]
	v_mfma_f32_16x16x32_bf16 v[46:49], v[156:159], v[202:205], v[46:49]
	v_mfma_f32_16x16x32_bf16 v[38:41], v[164:167], v[202:205], v[38:41]
	v_mfma_f32_16x16x32_bf16 v[30:33], v[156:159], v[210:213], v[30:33]
	v_mfma_f32_16x16x32_bf16 v[22:25], v[164:167], v[210:213], v[22:25]
	v_mfma_f32_16x16x32_bf16 v[14:17], v[156:159], v[218:221], v[14:17]
	v_mfma_f32_16x16x32_bf16 v[6:9], v[164:167], v[218:221], v[6:9]
	s_setprio 0
	s_setprio 1
	v_mfma_f32_16x16x32_bf16 v[58:61], v[172:175], v[188:191], v[58:61]
	v_mfma_f32_16x16x32_bf16 v[50:53], v[180:183], v[188:191], v[50:53]
	v_mfma_f32_16x16x32_bf16 v[42:45], v[172:175], v[198:201], v[42:45]
	v_mfma_f32_16x16x32_bf16 v[34:37], v[180:183], v[198:201], v[34:37]
	v_mfma_f32_16x16x32_bf16 v[26:29], v[172:175], v[206:209], v[26:29]
	v_mfma_f32_16x16x32_bf16 v[18:21], v[180:183], v[206:209], v[18:21]
	v_mfma_f32_16x16x32_bf16 v[10:13], v[172:175], v[214:217], v[10:13]
	v_mfma_f32_16x16x32_bf16 v[2:5], v[180:183], v[214:217], v[2:5]
	v_mfma_f32_16x16x32_bf16 v[58:61], v[176:179], v[192:195], v[58:61]
	v_mfma_f32_16x16x32_bf16 v[50:53], v[184:187], v[192:195], v[50:53]
	v_mfma_f32_16x16x32_bf16 v[42:45], v[176:179], v[202:205], v[42:45]
	v_mfma_f32_16x16x32_bf16 v[34:37], v[184:187], v[202:205], v[34:37]
	v_mfma_f32_16x16x32_bf16 v[26:29], v[176:179], v[210:213], v[26:29]
	v_mfma_f32_16x16x32_bf16 v[18:21], v[184:187], v[210:213], v[18:21]
	v_mfma_f32_16x16x32_bf16 v[10:13], v[176:179], v[218:221], v[10:13]
	v_mfma_f32_16x16x32_bf16 v[2:5], v[184:187], v[218:221], v[2:5]
	s_setprio 0
	s_barrier
	s_add_i32 s47, 0, 0x18000
	v_add_u32_e32 v155, s47, v150
	s_add_i32 s48, 0, 0x1c000
	ds_read_b128 v[146:149], v155
	ds_read_b128 v[156:159], v155 offset:1024
	ds_read_b128 v[160:163], v155 offset:2048
	ds_read_b128 v[164:167], v155 offset:3072
	v_add_u32_e32 v155, s48, v150
	ds_read_b128 v[172:175], v155
	ds_read_b128 v[176:179], v155 offset:1024
	ds_read_b128 v[180:183], v155 offset:2048
	ds_read_b128 v[184:187], v155 offset:3072
	s_add_u32 s16, s16, 0x40000
	s_addc_u32 s17, s17, 0
	s_mov_b32 m0, s34
	v_lshl_add_u64 v[230:231], s[16:17], 0, v[130:131]
	ds_read_b128 v[188:191], v154 offset:32768
	ds_read_b128 v[192:195], v154 offset:33792
	ds_read_b128 v[198:201], v154 offset:34816
	ds_read_b128 v[202:205], v154 offset:35840
	ds_read_b128 v[206:209], v154 offset:36864
	ds_read_b128 v[210:213], v154 offset:37888
	ds_read_b128 v[214:217], v154 offset:38912
	ds_read_b128 v[218:221], v154 offset:39936
	global_load_lds_dwordx4 v[230:231], off
	v_lshl_add_u64 v[230:231], s[16:17], 0, v[134:135]
	s_mov_b32 m0, s35
	s_nop 0
	global_load_lds_dwordx4 v[230:231], off
	s_waitcnt vmcnt(8)
	s_waitcnt lgkmcnt(0)
	v_mfma_f32_16x16x32_bf16 v[126:129], v[146:149], v[188:191], v[126:129]
	v_mfma_f32_16x16x32_bf16 v[118:121], v[160:163], v[188:191], v[118:121]
	v_mfma_f32_16x16x32_bf16 v[110:113], v[146:149], v[198:201], v[110:113]
	v_mfma_f32_16x16x32_bf16 v[102:105], v[160:163], v[198:201], v[102:105]
	s_barrier
	s_setprio 1
	s_waitcnt lgkmcnt(0)
	v_mfma_f32_16x16x32_bf16 v[94:97], v[146:149], v[206:209], v[94:97]
	v_mfma_f32_16x16x32_bf16 v[86:89], v[160:163], v[206:209], v[86:89]
	v_mfma_f32_16x16x32_bf16 v[78:81], v[146:149], v[214:217], v[78:81]
	v_mfma_f32_16x16x32_bf16 v[70:73], v[160:163], v[214:217], v[70:73]
	v_mfma_f32_16x16x32_bf16 v[126:129], v[156:159], v[192:195], v[126:129]
	v_mfma_f32_16x16x32_bf16 v[118:121], v[164:167], v[192:195], v[118:121]
	v_mfma_f32_16x16x32_bf16 v[110:113], v[156:159], v[202:205], v[110:113]
	v_mfma_f32_16x16x32_bf16 v[102:105], v[164:167], v[202:205], v[102:105]
	v_mfma_f32_16x16x32_bf16 v[94:97], v[156:159], v[210:213], v[94:97]
	v_mfma_f32_16x16x32_bf16 v[86:89], v[164:167], v[210:213], v[86:89]
	v_mfma_f32_16x16x32_bf16 v[78:81], v[156:159], v[218:221], v[78:81]
	v_mfma_f32_16x16x32_bf16 v[70:73], v[164:167], v[218:221], v[70:73]
	s_setprio 0
	s_setprio 1
	v_mfma_f32_16x16x32_bf16 v[122:125], v[172:175], v[188:191], v[122:125]
	v_mfma_f32_16x16x32_bf16 v[114:117], v[180:183], v[188:191], v[114:117]
	v_mfma_f32_16x16x32_bf16 v[106:109], v[172:175], v[198:201], v[106:109]
	v_mfma_f32_16x16x32_bf16 v[98:101], v[180:183], v[198:201], v[98:101]
	v_mfma_f32_16x16x32_bf16 v[90:93], v[172:175], v[206:209], v[90:93]
	v_mfma_f32_16x16x32_bf16 v[82:85], v[180:183], v[206:209], v[82:85]
	v_mfma_f32_16x16x32_bf16 v[74:77], v[172:175], v[214:217], v[74:77]
	v_mfma_f32_16x16x32_bf16 v[66:69], v[180:183], v[214:217], v[66:69]
	v_mfma_f32_16x16x32_bf16 v[122:125], v[176:179], v[192:195], v[122:125]
	v_mfma_f32_16x16x32_bf16 v[114:117], v[184:187], v[192:195], v[114:117]
	v_mfma_f32_16x16x32_bf16 v[106:109], v[176:179], v[202:205], v[106:109]
	v_mfma_f32_16x16x32_bf16 v[98:101], v[184:187], v[202:205], v[98:101]
	v_mfma_f32_16x16x32_bf16 v[90:93], v[176:179], v[210:213], v[90:93]
	v_mfma_f32_16x16x32_bf16 v[82:85], v[184:187], v[210:213], v[82:85]
	v_mfma_f32_16x16x32_bf16 v[74:77], v[176:179], v[218:221], v[74:77]
	v_mfma_f32_16x16x32_bf16 v[66:69], v[184:187], v[218:221], v[66:69]
	s_setprio 0
	s_barrier
; #define PG8_STAGE(bufoff, gbase, voff) do { _Pragma("unroll") for (int _i = 0; _i < 2; ++_i) \
;         __builtin_amdgcn_global_load_lds((const unsigned*)((const char*)(gbase) + (voff)[_i]), (PG8_LAS unsigned*)(lds + (bufoff) + ldsw + _i * 8192), 16, 0, 0); } while (0)
; #define PG8_LDA(dst, b, h) do { _Pragma("unroll") for (int m = 0; m < 4; ++m) _Pragma("unroll") for (int k = 0; k < 2; ++k) dst[m][k] = *(const PG8_LAS bf16x8*)(lds + PG8_SA(b, h) + aoff + m * 2048 + k * 1024); } while (0)
; #define PG8_MMA(ai, bj, At, Bt) do { __builtin_amdgcn_s_setprio(1); _Pragma("unroll") for (int m = 0; m < 4; ++m) _Pragma("unroll") for (int n = 0; n < 2; ++n) _Pragma("unroll") for (int k = 0; k < 2; ++k) \
;         acc[ai][bj][m][n] = __builtin_amdgcn_mfma_f32_16x16x32_bf16(Bt[n][k], At[m][k], acc[ai][bj][m][n], 0, 0, 0); __builtin_amdgcn_s_setprio(0); } while (0)
; #define PG8_WAIT_V(n) asm volatile("s_waitcnt vmcnt(" #n ")" ::: "memory")
; #define PG8_WAIT_L(n) asm volatile("s_waitcnt lgkmcnt(" #n ")" ::: "memory")
; #define PG8_BAR __builtin_amdgcn_s_barrier()
; #define PG8_SCHED __builtin_amdgcn_sched_barrier(0)
; template <class Epi, class Sched, bool ALIGN_EPI = false, bool SP2 = false>
; __device__ __forceinline__ void gemm_phase(PG8_LAS unsigned char* lds, const Gemm g, const Sched& S, const Epi& E) {
;     ...
;         for (int t = 0; t < nt; t += 2) {
;     ...
;             PG8_WAIT_V(8); PG8_WAIT_L(0); PG8_BAR; PG8_MMA(0, 0, At, B0); PG8_MMA(0, 1, At, B1); PG8_BAR; PG8_SCHED;
;             PG8_LDA(At, 1, 1); PG8_STAGE(PG8_SB(1, 0), b3, voffB); PG8_STAGE(PG8_SB(1, 1), b3 + hstep, voffB); PG8_STAGE(PG8_SA(1, 0), a3, voffA);
;             PG8_WAIT_V(8); PG8_WAIT_L(0); PG8_BAR; PG8_MMA(1, 0, At, B0); PG8_MMA(1, 1, At, B1); PG8_BAR; PG8_SCHED;
	s_add_i32 s16, s47, s27
	v_lshl_add_u64 v[222:223], v[222:223], 0, s[6:7]
	s_mov_b32 m0, s16
	ds_read_b128 v[188:191], v154 offset:49152
	ds_read_b128 v[192:195], v154 offset:50176
	ds_read_b128 v[198:201], v154 offset:51200
	ds_read_b128 v[202:205], v154 offset:52224
	ds_read_b128 v[206:209], v154 offset:53248
	ds_read_b128 v[210:213], v154 offset:54272
	ds_read_b128 v[214:217], v154 offset:55296
	ds_read_b128 v[218:221], v154 offset:56320
	global_load_lds_dwordx4 v[222:223], off
	s_add_i32 m0, s16, 0x2000
	s_add_u32 s2, s2, 0x40080
	v_lshl_add_u64 v[222:223], v[224:225], 0, s[6:7]
	s_addc_u32 s3, s3, 0
	s_add_i32 s16, s48, s27
	global_load_lds_dwordx4 v[222:223], off
	v_lshl_add_u64 v[222:223], s[2:3], 0, v[132:133]
	s_mov_b32 m0, s16
	s_nop 0
	global_load_lds_dwordx4 v[222:223], off
	v_lshl_add_u64 v[222:223], s[2:3], 0, v[136:137]
	s_add_i32 m0, s16, 0x2000
	s_nop 0
	global_load_lds_dwordx4 v[222:223], off
	v_lshl_add_u64 v[222:223], v[226:227], 0, s[6:7]
	s_mov_b32 m0, s37
	s_nop 0
	global_load_lds_dwordx4 v[222:223], off
	v_lshl_add_u64 v[222:223], v[228:229], 0, s[6:7]
	s_mov_b32 m0, s38
	s_nop 0
	global_load_lds_dwordx4 v[222:223], off
	s_waitcnt vmcnt(8)
	s_waitcnt lgkmcnt(0)
	v_mfma_f32_16x16x32_bf16 v[62:65], v[146:149], v[188:191], v[62:65]
	v_mfma_f32_16x16x32_bf16 v[54:57], v[160:163], v[188:191], v[54:57]
	v_mfma_f32_16x16x32_bf16 v[46:49], v[146:149], v[198:201], v[46:49]
	v_mfma_f32_16x16x32_bf16 v[38:41], v[160:163], v[198:201], v[38:41]
	s_barrier
	s_setprio 1
	s_waitcnt lgkmcnt(0)
	v_mfma_f32_16x16x32_bf16 v[30:33], v[146:149], v[206:209], v[30:33]
	v_mfma_f32_16x16x32_bf16 v[22:25], v[160:163], v[206:209], v[22:25]
	v_mfma_f32_16x16x32_bf16 v[14:17], v[146:149], v[214:217], v[14:17]
	v_mfma_f32_16x16x32_bf16 v[6:9], v[160:163], v[214:217], v[6:9]
	v_mfma_f32_16x16x32_bf16 v[62:65], v[156:159], v[192:195], v[62:65]
	v_mfma_f32_16x16x32_bf16 v[54:57], v[164:167], v[192:195], v[54:57]
	v_mfma_f32_16x16x32_bf16 v[46:49], v[156:159], v[202:205], v[46:49]
	v_mfma_f32_16x16x32_bf16 v[38:41], v[164:167], v[202:205], v[38:41]
	v_mfma_f32_16x16x32_bf16 v[30:33], v[156:159], v[210:213], v[30:33]
	v_mfma_f32_16x16x32_bf16 v[22:25], v[164:167], v[210:213], v[22:25]
	v_mfma_f32_16x16x32_bf16 v[14:17], v[156:159], v[218:221], v[14:17]
	v_mfma_f32_16x16x32_bf16 v[6:9], v[164:167], v[218:221], v[6:9]
	s_setprio 0
	s_setprio 1
	v_mfma_f32_16x16x32_bf16 v[58:61], v[172:175], v[188:191], v[58:61]
	v_mfma_f32_16x16x32_bf16 v[50:53], v[180:183], v[188:191], v[50:53]
	v_mfma_f32_16x16x32_bf16 v[42:45], v[172:175], v[198:201], v[42:45]
	v_mfma_f32_16x16x32_bf16 v[34:37], v[180:183], v[198:201], v[34:37]
	v_mfma_f32_16x16x32_bf16 v[26:29], v[172:175], v[206:209], v[26:29]
	v_mfma_f32_16x16x32_bf16 v[18:21], v[180:183], v[206:209], v[18:21]
	v_mfma_f32_16x16x32_bf16 v[10:13], v[172:175], v[214:217], v[10:13]
	v_mfma_f32_16x16x32_bf16 v[2:5], v[180:183], v[214:217], v[2:5]
	v_mfma_f32_16x16x32_bf16 v[58:61], v[176:179], v[192:195], v[58:61]
	v_mfma_f32_16x16x32_bf16 v[50:53], v[184:187], v[192:195], v[50:53]
	v_mfma_f32_16x16x32_bf16 v[42:45], v[176:179], v[202:205], v[42:45]
	v_mfma_f32_16x16x32_bf16 v[34:37], v[184:187], v[202:205], v[34:37]
	v_mfma_f32_16x16x32_bf16 v[26:29], v[176:179], v[210:213], v[26:29]
	v_mfma_f32_16x16x32_bf16 v[18:21], v[184:187], v[210:213], v[18:21]
	v_mfma_f32_16x16x32_bf16 v[10:13], v[176:179], v[218:221], v[10:13]
	v_mfma_f32_16x16x32_bf16 v[2:5], v[184:187], v[218:221], v[2:5]
	s_setprio 0
	s_barrier
	s_add_i32 s46, s46, 2
	s_add_u32 s28, s28, 0x100
	s_addc_u32 s29, s29, 0
	s_add_u32 s30, s30, 0x100
	s_addc_u32 s31, s31, 0
	s_cmp_gt_u32 s46, 13
	s_cbranch_scc0 .LBB0_102
	s_and_b64 vcc, exec, s[12:13]
	s_cbranch_vccz .LBB0_105
	s_barrier

; #define PG8_STAGE(bufoff, gbase, voff) do { _Pragma("unroll") for (int _i = 0; _i < 2; ++_i) \
;         __builtin_amdgcn_global_load_lds((const unsigned*)((const char*)(gbase) + (voff)[_i]), (PG8_LAS unsigned*)(lds + (bufoff) + ldsw + _i * 8192), 16, 0, 0); } while (0)
; #define PG8_LDA(dst, b, h) do { _Pragma("unroll") for (int m = 0; m < 4; ++m) _Pragma("unroll") for (int k = 0; k < 2; ++k) dst[m][k] = *(const PG8_LAS bf16x8*)(lds + PG8_SA(b, h) + aoff + m * 2048 + k * 1024); } while (0)
; #define PG8_LDB(dst, b, h) do { _Pragma("unroll") for (int n = 0; n < 2; ++n) _Pragma("unroll") for (int k = 0; k < 2; ++k) dst[n][k] = *(const PG8_LAS bf16x8*)(lds + PG8_SB(b, h) + boff + n * 2048 + k * 1024); } while (0)
; #define PG8_MMA(ai, bj, At, Bt) do { __builtin_amdgcn_s_setprio(1); _Pragma("unroll") for (int m = 0; m < 4; ++m) _Pragma("unroll") for (int n = 0; n < 2; ++n) _Pragma("unroll") for (int k = 0; k < 2; ++k) \
;         acc[ai][bj][m][n] = __builtin_amdgcn_mfma_f32_16x16x32_bf16(Bt[n][k], At[m][k], acc[ai][bj][m][n], 0, 0, 0); __builtin_amdgcn_s_setprio(0); } while (0)
; #define PG8_WAIT_V(n) asm volatile("s_waitcnt vmcnt(" #n ")" ::: "memory")
; #define PG8_WAIT_L(n) asm volatile("s_waitcnt lgkmcnt(" #n ")" ::: "memory")
; #define PG8_BAR __builtin_amdgcn_s_barrier()
; #define PG8_SCHED __builtin_amdgcn_sched_barrier(0)
; template <class Epi, class Sched, bool ALIGN_EPI = false, bool SP2 = false>
; __device__ __forceinline__ void gemm_phase(PG8_LAS unsigned char* lds, const Gemm g, const Sched& S, const Epi& E) {
;     ...
;             if constexpr (SP2) {
;             PG8_LDB(B0, 0, 0); PG8_LDB(B1, 0, 1); PG8_SCHED; PG8_LDA(At, 0, 0); PG8_STAGE(PG8_SA(1, 1), a1 + hstep, voffA);
;             PG8_WAIT_V(8); PG8_WAIT_L(0); PG8_BAR; PG8_MMA(0, 0, At, B0); PG8_MMA(0, 1, At, B1); PG8_BAR; PG8_SCHED;
;             PG8_LDA(At, 0, 1); PG8_STAGE(PG8_SB(0, 0), b2, voffB); PG8_STAGE(PG8_SB(0, 1), b2 + hstep, voffB); PG8_STAGE(PG8_SA(0, 0), a2, voffA);
;             PG8_WAIT_V(8); PG8_WAIT_L(0); PG8_BAR; PG8_MMA(1, 0, At, B0); PG8_MMA(1, 1, At, B1); PG8_BAR; PG8_SCHED;
.LBB0_187:
	v_add_u32_e32 v155, s40, v153
	ds_read_b128 v[156:159], v155
	ds_read_b128 v[160:163], v155 offset:1024
	ds_read_b128 v[164:167], v155 offset:2048
	ds_read_b128 v[172:175], v155 offset:3072
	v_add_u32_e32 v155, s41, v153
	s_add_u32 s2, s12, s22
	ds_read_b128 v[176:179], v155
	ds_read_b128 v[180:183], v155 offset:1024
	ds_read_b128 v[184:187], v155 offset:2048
	ds_read_b128 v[188:191], v155 offset:3072
	s_addc_u32 s3, s13, s23
	s_add_u32 s2, s2, 0x100
	s_addc_u32 s3, s3, 0
	s_add_u32 s49, s45, s22
	s_addc_u32 s52, s46, s23
	s_cmpk_eq_i32 s22, 0x1500
	s_cselect_b32 s17, s21, s3
	s_cselect_b32 s16, s20, s2
	s_cselect_b32 s3, s1, s52
	s_cselect_b32 s2, s0, s49
	v_lshl_add_u64 v[226:227], v[148:149], 0, s[22:23]
	s_add_i32 m0, s30, 0xc000
	ds_read_b128 v[192:195], v154
	ds_read_b128 v[198:201], v154 offset:1024
	ds_read_b128 v[202:205], v154 offset:2048
	ds_read_b128 v[206:209], v154 offset:3072
	ds_read_b128 v[210:213], v154 offset:4096
	ds_read_b128 v[214:217], v154 offset:5120
	ds_read_b128 v[218:221], v154 offset:6144
	ds_read_b128 v[222:225], v154 offset:7168
	global_load_lds_dwordx4 v[226:227], off
	v_lshl_add_u64 v[226:227], v[150:151], 0, s[22:23]
	s_add_i32 m0, s30, 0xe000
	s_nop 0
	global_load_lds_dwordx4 v[226:227], off
	s_waitcnt vmcnt(8)
	s_waitcnt lgkmcnt(0)
	v_mfma_f32_16x16x32_bf16 v[112:115], v[156:159], v[192:195], v[112:115]
	v_mfma_f32_16x16x32_bf16 v[124:127], v[164:167], v[192:195], v[124:127]
	v_mfma_f32_16x16x32_bf16 v[96:99], v[156:159], v[202:205], v[96:99]
	v_mfma_f32_16x16x32_bf16 v[128:131], v[164:167], v[202:205], v[128:131]
	s_barrier
	s_setprio 1
	s_waitcnt lgkmcnt(0)
	v_mfma_f32_16x16x32_bf16 v[100:103], v[156:159], v[210:213], v[100:103]
	v_mfma_f32_16x16x32_bf16 v[116:119], v[164:167], v[210:213], v[116:119]
	v_mfma_f32_16x16x32_bf16 v[104:107], v[156:159], v[218:221], v[104:107]
	v_mfma_f32_16x16x32_bf16 v[120:123], v[164:167], v[218:221], v[120:123]
	v_mfma_f32_16x16x32_bf16 v[112:115], v[160:163], v[198:201], v[112:115]
	v_mfma_f32_16x16x32_bf16 v[124:127], v[172:175], v[198:201], v[124:127]
	v_mfma_f32_16x16x32_bf16 v[96:99], v[160:163], v[206:209], v[96:99]
	v_mfma_f32_16x16x32_bf16 v[128:131], v[172:175], v[206:209], v[128:131]
	v_mfma_f32_16x16x32_bf16 v[100:103], v[160:163], v[214:217], v[100:103]
	v_mfma_f32_16x16x32_bf16 v[116:119], v[172:175], v[214:217], v[116:119]
	v_mfma_f32_16x16x32_bf16 v[104:107], v[160:163], v[222:225], v[104:107]
	v_mfma_f32_16x16x32_bf16 v[120:123], v[172:175], v[222:225], v[120:123]
	s_setprio 0
	s_setprio 1
	v_mfma_f32_16x16x32_bf16 v[108:111], v[176:179], v[192:195], v[108:111]
	v_mfma_f32_16x16x32_bf16 v[92:95], v[184:187], v[192:195], v[92:95]
	v_mfma_f32_16x16x32_bf16 v[80:83], v[176:179], v[202:205], v[80:83]
	v_mfma_f32_16x16x32_bf16 v[68:71], v[184:187], v[202:205], v[68:71]
	v_mfma_f32_16x16x32_bf16 v[84:87], v[176:179], v[210:213], v[84:87]
	v_mfma_f32_16x16x32_bf16 v[72:75], v[184:187], v[210:213], v[72:75]
	v_mfma_f32_16x16x32_bf16 v[88:91], v[176:179], v[218:221], v[88:91]
	v_mfma_f32_16x16x32_bf16 v[76:79], v[184:187], v[218:221], v[76:79]
	v_mfma_f32_16x16x32_bf16 v[108:111], v[180:183], v[198:201], v[108:111]
	v_mfma_f32_16x16x32_bf16 v[92:95], v[188:191], v[198:201], v[92:95]
	v_mfma_f32_16x16x32_bf16 v[80:83], v[180:183], v[206:209], v[80:83]
	v_mfma_f32_16x16x32_bf16 v[68:71], v[188:191], v[206:209], v[68:71]
	v_mfma_f32_16x16x32_bf16 v[84:87], v[180:183], v[214:217], v[84:87]
	v_mfma_f32_16x16x32_bf16 v[72:75], v[188:191], v[214:217], v[72:75]
	v_mfma_f32_16x16x32_bf16 v[88:91], v[180:183], v[222:225], v[88:91]
	v_mfma_f32_16x16x32_bf16 v[76:79], v[188:191], v[222:225], v[76:79]
	s_setprio 0
	s_barrier
	s_add_i32 s49, s40, s29
	v_lshl_add_u64 v[226:227], s[2:3], 0, v[134:135]
	s_mov_b32 m0, s49
	ds_read_b128 v[192:195], v154 offset:16384
	ds_read_b128 v[198:201], v154 offset:17408
	ds_read_b128 v[202:205], v154 offset:18432
	ds_read_b128 v[206:209], v154 offset:19456
	ds_read_b128 v[210:213], v154 offset:20480
	ds_read_b128 v[214:217], v154 offset:21504
	ds_read_b128 v[218:221], v154 offset:22528
	ds_read_b128 v[222:225], v154 offset:23552
	global_load_lds_dwordx4 v[226:227], off
	s_add_i32 m0, s49, 0x2000
	s_add_u32 s52, s2, 0xb0000
	v_lshl_add_u64 v[228:229], s[2:3], 0, v[138:139]
	s_addc_u32 s53, s3, 0
	s_add_i32 s49, s41, s29
	global_load_lds_dwordx4 v[228:229], off
	v_lshl_add_u64 v[230:231], s[52:53], 0, v[134:135]
	s_mov_b32 m0, s49
	v_lshl_add_u64 v[232:233], s[16:17], 0, v[136:137]
	global_load_lds_dwordx4 v[230:231], off
	v_lshl_add_u64 v[230:231], s[52:53], 0, v[138:139]
	s_add_i32 m0, s49, 0x2000
	s_nop 0
	global_load_lds_dwordx4 v[230:231], off
	v_lshl_add_u64 v[230:231], s[16:17], 0, v[132:133]
	s_mov_b32 m0, s30
	s_nop 0
	global_load_lds_dwordx4 v[230:231], off
	s_mov_b32 m0, s31
	s_nop 0
	global_load_lds_dwordx4 v[232:233], off
	s_waitcnt vmcnt(8)
	s_waitcnt lgkmcnt(0)
	v_mfma_f32_16x16x32_bf16 v[64:67], v[156:159], v[192:195], v[64:67]
	v_mfma_f32_16x16x32_bf16 v[60:63], v[164:167], v[192:195], v[60:63]
	v_mfma_f32_16x16x32_bf16 v[48:51], v[156:159], v[202:205], v[48:51]
	v_mfma_f32_16x16x32_bf16 v[44:47], v[164:167], v[202:205], v[44:47]
	s_barrier
; #define PG8_STAGE(bufoff, gbase, voff) do { _Pragma("unroll") for (int _i = 0; _i < 2; ++_i) \
;         __builtin_amdgcn_global_load_lds((const unsigned*)((const char*)(gbase) + (voff)[_i]), (PG8_LAS unsigned*)(lds + (bufoff) + ldsw + _i * 8192), 16, 0, 0); } while (0)
; #define PG8_LDA(dst, b, h) do { _Pragma("unroll") for (int m = 0; m < 4; ++m) _Pragma("unroll") for (int k = 0; k < 2; ++k) dst[m][k] = *(const PG8_LAS bf16x8*)(lds + PG8_SA(b, h) + aoff + m * 2048 + k * 1024); } while (0)
; #define PG8_LDB(dst, b, h) do { _Pragma("unroll") for (int n = 0; n < 2; ++n) _Pragma("unroll") for (int k = 0; k < 2; ++k) dst[n][k] = *(const PG8_LAS bf16x8*)(lds + PG8_SB(b, h) + boff + n * 2048 + k * 1024); } while (0)
; #define PG8_MMA(ai, bj, At, Bt) do { __builtin_amdgcn_s_setprio(1); _Pragma("unroll") for (int m = 0; m < 4; ++m) _Pragma("unroll") for (int n = 0; n < 2; ++n) _Pragma("unroll") for (int k = 0; k < 2; ++k) \
;         acc[ai][bj][m][n] = __builtin_amdgcn_mfma_f32_16x16x32_bf16(Bt[n][k], At[m][k], acc[ai][bj][m][n], 0, 0, 0); __builtin_amdgcn_s_setprio(0); } while (0)
; #define PG8_WAIT_V(n) asm volatile("s_waitcnt vmcnt(" #n ")" ::: "memory")
; #define PG8_WAIT_L(n) asm volatile("s_waitcnt lgkmcnt(" #n ")" ::: "memory")
; #define PG8_BAR __builtin_amdgcn_s_barrier()
; #define PG8_SCHED __builtin_amdgcn_sched_barrier(0)
; template <class Epi, class Sched, bool ALIGN_EPI = false, bool SP2 = false>
; __device__ __forceinline__ void gemm_phase(PG8_LAS unsigned char* lds, const Gemm g, const Sched& S, const Epi& E) {
;     ...
;             PG8_WAIT_V(8); PG8_WAIT_L(0); PG8_BAR; PG8_MMA(1, 0, At, B0); PG8_MMA(1, 1, At, B1); PG8_BAR; PG8_SCHED;
;             PG8_LDB(B0, 1, 0); PG8_LDB(B1, 1, 1); PG8_SCHED; PG8_LDA(At, 1, 0); PG8_STAGE(PG8_SA(0, 1), a2 + hstep, voffA);
;             PG8_WAIT_V(8); PG8_WAIT_L(0); PG8_BAR; PG8_MMA(0, 0, At, B0); PG8_MMA(0, 1, At, B1); PG8_BAR; PG8_SCHED;
	s_setprio 1
	s_waitcnt lgkmcnt(0)
	v_mfma_f32_16x16x32_bf16 v[32:35], v[156:159], v[210:213], v[32:35]
	v_mfma_f32_16x16x32_bf16 v[28:31], v[164:167], v[210:213], v[28:31]
	v_mfma_f32_16x16x32_bf16 v[16:19], v[156:159], v[218:221], v[16:19]
	v_mfma_f32_16x16x32_bf16 v[12:15], v[164:167], v[218:221], v[12:15]
	v_mfma_f32_16x16x32_bf16 v[64:67], v[160:163], v[198:201], v[64:67]
	v_mfma_f32_16x16x32_bf16 v[60:63], v[172:175], v[198:201], v[60:63]
	v_mfma_f32_16x16x32_bf16 v[48:51], v[160:163], v[206:209], v[48:51]
	v_mfma_f32_16x16x32_bf16 v[44:47], v[172:175], v[206:209], v[44:47]
	v_mfma_f32_16x16x32_bf16 v[32:35], v[160:163], v[214:217], v[32:35]
	v_mfma_f32_16x16x32_bf16 v[28:31], v[172:175], v[214:217], v[28:31]
	v_mfma_f32_16x16x32_bf16 v[16:19], v[160:163], v[222:225], v[16:19]
	v_mfma_f32_16x16x32_bf16 v[12:15], v[172:175], v[222:225], v[12:15]
	s_setprio 0
	s_setprio 1
	v_mfma_f32_16x16x32_bf16 v[56:59], v[176:179], v[192:195], v[56:59]
	v_mfma_f32_16x16x32_bf16 v[52:55], v[184:187], v[192:195], v[52:55]
	v_mfma_f32_16x16x32_bf16 v[40:43], v[176:179], v[202:205], v[40:43]
	v_mfma_f32_16x16x32_bf16 v[36:39], v[184:187], v[202:205], v[36:39]
	v_mfma_f32_16x16x32_bf16 v[24:27], v[176:179], v[210:213], v[24:27]
	v_mfma_f32_16x16x32_bf16 v[20:23], v[184:187], v[210:213], v[20:23]
	v_mfma_f32_16x16x32_bf16 v[8:11], v[176:179], v[218:221], v[8:11]
	v_mfma_f32_16x16x32_bf16 v[4:7], v[184:187], v[218:221], v[4:7]
	v_mfma_f32_16x16x32_bf16 v[56:59], v[180:183], v[198:201], v[56:59]
	v_mfma_f32_16x16x32_bf16 v[52:55], v[188:191], v[198:201], v[52:55]
	v_mfma_f32_16x16x32_bf16 v[40:43], v[180:183], v[206:209], v[40:43]
	v_mfma_f32_16x16x32_bf16 v[36:39], v[188:191], v[206:209], v[36:39]
	v_mfma_f32_16x16x32_bf16 v[24:27], v[180:183], v[214:217], v[24:27]
	v_mfma_f32_16x16x32_bf16 v[20:23], v[188:191], v[214:217], v[20:23]
	v_mfma_f32_16x16x32_bf16 v[8:11], v[180:183], v[222:225], v[8:11]
	v_mfma_f32_16x16x32_bf16 v[4:7], v[188:191], v[222:225], v[4:7]
	s_setprio 0
	s_barrier
	s_add_i32 s49, 0, 0x18000
	v_add_u32_e32 v155, s49, v153
	s_add_i32 s52, 0, 0x1c000
	ds_read_b128 v[156:159], v155
	ds_read_b128 v[160:163], v155 offset:1024
	ds_read_b128 v[164:167], v155 offset:2048
	ds_read_b128 v[172:175], v155 offset:3072
	v_add_u32_e32 v155, s52, v153
	ds_read_b128 v[176:179], v155
	ds_read_b128 v[180:183], v155 offset:1024
	ds_read_b128 v[184:187], v155 offset:2048
	ds_read_b128 v[188:191], v155 offset:3072
	s_add_u32 s16, s16, 0xb0000
	s_addc_u32 s17, s17, 0
	s_mov_b32 m0, s34
	v_lshl_add_u64 v[234:235], s[16:17], 0, v[132:133]
	ds_read_b128 v[192:195], v154 offset:32768
	ds_read_b128 v[198:201], v154 offset:33792
	ds_read_b128 v[202:205], v154 offset:34816
	ds_read_b128 v[206:209], v154 offset:35840
	ds_read_b128 v[210:213], v154 offset:36864
	ds_read_b128 v[214:217], v154 offset:37888
	ds_read_b128 v[218:221], v154 offset:38912
	ds_read_b128 v[222:225], v154 offset:39936
	global_load_lds_dwordx4 v[234:235], off
	v_lshl_add_u64 v[234:235], s[16:17], 0, v[136:137]
	s_mov_b32 m0, s35
	s_nop 0
	global_load_lds_dwordx4 v[234:235], off
	s_waitcnt vmcnt(8)
	s_waitcnt lgkmcnt(0)
	v_mfma_f32_16x16x32_bf16 v[112:115], v[156:159], v[192:195], v[112:115]
	v_mfma_f32_16x16x32_bf16 v[124:127], v[164:167], v[192:195], v[124:127]
	v_mfma_f32_16x16x32_bf16 v[96:99], v[156:159], v[202:205], v[96:99]
	v_mfma_f32_16x16x32_bf16 v[128:131], v[164:167], v[202:205], v[128:131]
	s_barrier
	s_setprio 1
	s_waitcnt lgkmcnt(0)
	v_mfma_f32_16x16x32_bf16 v[100:103], v[156:159], v[210:213], v[100:103]
	v_mfma_f32_16x16x32_bf16 v[116:119], v[164:167], v[210:213], v[116:119]
	v_mfma_f32_16x16x32_bf16 v[104:107], v[156:159], v[218:221], v[104:107]
	v_mfma_f32_16x16x32_bf16 v[120:123], v[164:167], v[218:221], v[120:123]
	v_mfma_f32_16x16x32_bf16 v[112:115], v[160:163], v[198:201], v[112:115]
	v_mfma_f32_16x16x32_bf16 v[124:127], v[172:175], v[198:201], v[124:127]
	v_mfma_f32_16x16x32_bf16 v[96:99], v[160:163], v[206:209], v[96:99]
	v_mfma_f32_16x16x32_bf16 v[128:131], v[172:175], v[206:209], v[128:131]
	v_mfma_f32_16x16x32_bf16 v[100:103], v[160:163], v[214:217], v[100:103]
	v_mfma_f32_16x16x32_bf16 v[116:119], v[172:175], v[214:217], v[116:119]
	v_mfma_f32_16x16x32_bf16 v[104:107], v[160:163], v[222:225], v[104:107]
	v_mfma_f32_16x16x32_bf16 v[120:123], v[172:175], v[222:225], v[120:123]
	s_setprio 0
	s_setprio 1
	v_mfma_f32_16x16x32_bf16 v[108:111], v[176:179], v[192:195], v[108:111]
	v_mfma_f32_16x16x32_bf16 v[92:95], v[184:187], v[192:195], v[92:95]
	v_mfma_f32_16x16x32_bf16 v[80:83], v[176:179], v[202:205], v[80:83]
	v_mfma_f32_16x16x32_bf16 v[68:71], v[184:187], v[202:205], v[68:71]
	v_mfma_f32_16x16x32_bf16 v[84:87], v[176:179], v[210:213], v[84:87]
	v_mfma_f32_16x16x32_bf16 v[72:75], v[184:187], v[210:213], v[72:75]
	v_mfma_f32_16x16x32_bf16 v[88:91], v[176:179], v[218:221], v[88:91]
	v_mfma_f32_16x16x32_bf16 v[76:79], v[184:187], v[218:221], v[76:79]
	v_mfma_f32_16x16x32_bf16 v[108:111], v[180:183], v[198:201], v[108:111]
	v_mfma_f32_16x16x32_bf16 v[92:95], v[188:191], v[198:201], v[92:95]
	v_mfma_f32_16x16x32_bf16 v[80:83], v[180:183], v[206:209], v[80:83]
	v_mfma_f32_16x16x32_bf16 v[68:71], v[188:191], v[206:209], v[68:71]
	v_mfma_f32_16x16x32_bf16 v[84:87], v[180:183], v[214:217], v[84:87]
	v_mfma_f32_16x16x32_bf16 v[72:75], v[188:191], v[214:217], v[72:75]
	v_mfma_f32_16x16x32_bf16 v[88:91], v[180:183], v[222:225], v[88:91]
	v_mfma_f32_16x16x32_bf16 v[76:79], v[188:191], v[222:225], v[76:79]
	s_setprio 0
	s_barrier
; #define PG8_STAGE(bufoff, gbase, voff) do { _Pragma("unroll") for (int _i = 0; _i < 2; ++_i) \
;         __builtin_amdgcn_global_load_lds((const unsigned*)((const char*)(gbase) + (voff)[_i]), (PG8_LAS unsigned*)(lds + (bufoff) + ldsw + _i * 8192), 16, 0, 0); } while (0)
; #define PG8_LDA(dst, b, h) do { _Pragma("unroll") for (int m = 0; m < 4; ++m) _Pragma("unroll") for (int k = 0; k < 2; ++k) dst[m][k] = *(const PG8_LAS bf16x8*)(lds + PG8_SA(b, h) + aoff + m * 2048 + k * 1024); } while (0)
; #define PG8_MMA(ai, bj, At, Bt) do { __builtin_amdgcn_s_setprio(1); _Pragma("unroll") for (int m = 0; m < 4; ++m) _Pragma("unroll") for (int n = 0; n < 2; ++n) _Pragma("unroll") for (int k = 0; k < 2; ++k) \
;         acc[ai][bj][m][n] = __builtin_amdgcn_mfma_f32_16x16x32_bf16(Bt[n][k], At[m][k], acc[ai][bj][m][n], 0, 0, 0); __builtin_amdgcn_s_setprio(0); } while (0)
; #define PG8_WAIT_V(n) asm volatile("s_waitcnt vmcnt(" #n ")" ::: "memory")
; #define PG8_WAIT_L(n) asm volatile("s_waitcnt lgkmcnt(" #n ")" ::: "memory")
; #define PG8_BAR __builtin_amdgcn_s_barrier()
; #define PG8_SCHED __builtin_amdgcn_sched_barrier(0)
; template <class Epi, class Sched, bool ALIGN_EPI = false, bool SP2 = false>
; __device__ __forceinline__ void gemm_phase(PG8_LAS unsigned char* lds, const Gemm g, const Sched& S, const Epi& E) {
;     ...
;             PG8_LDA(At, 1, 1); PG8_STAGE(PG8_SB(1, 0), b3, voffB); PG8_STAGE(PG8_SB(1, 1), b3 + hstep, voffB); PG8_STAGE(PG8_SA(1, 0), a3, voffA);
;             PG8_WAIT_V(8); PG8_WAIT_L(0); PG8_BAR; PG8_MMA(1, 0, At, B0); PG8_MMA(1, 1, At, B1); PG8_BAR; PG8_SCHED;
;     ...
;         if (!has_next) break;
; #pragma unroll
;         for (int a = 0; a < 2; ++a)
; #pragma unroll
;             for (int b = 0; b < 2; ++b)
; #pragma unroll
;                 for (int m = 0; m < 4; ++m)
; #pragma unroll
;                     for (int n = 0; n < 2; ++n) acc[a][b][m][n] = (f32x4){0.f, 0.f, 0.f, 0.f};
	s_add_i32 s16, s49, s29
	v_lshl_add_u64 v[226:227], v[226:227], 0, s[14:15]
	s_mov_b32 m0, s16
	ds_read_b128 v[192:195], v154 offset:49152
	ds_read_b128 v[198:201], v154 offset:50176
	ds_read_b128 v[202:205], v154 offset:51200
	ds_read_b128 v[206:209], v154 offset:52224
	ds_read_b128 v[210:213], v154 offset:53248
	ds_read_b128 v[214:217], v154 offset:54272
	ds_read_b128 v[218:221], v154 offset:55296
	ds_read_b128 v[222:225], v154 offset:56320
	global_load_lds_dwordx4 v[226:227], off
	s_add_i32 m0, s16, 0x2000
	s_add_u32 s2, s2, 0xb0080
	v_lshl_add_u64 v[226:227], v[228:229], 0, s[14:15]
	s_addc_u32 s3, s3, 0
	s_add_i32 s16, s52, s29
	global_load_lds_dwordx4 v[226:227], off
	v_lshl_add_u64 v[226:227], s[2:3], 0, v[134:135]
	s_mov_b32 m0, s16
	s_nop 0
	global_load_lds_dwordx4 v[226:227], off
	v_lshl_add_u64 v[226:227], s[2:3], 0, v[138:139]
	s_add_i32 m0, s16, 0x2000
	s_nop 0
	global_load_lds_dwordx4 v[226:227], off
	v_lshl_add_u64 v[226:227], v[230:231], 0, s[14:15]
	s_mov_b32 m0, s38
	s_nop 0
	global_load_lds_dwordx4 v[226:227], off
	v_lshl_add_u64 v[226:227], v[232:233], 0, s[14:15]
	s_mov_b32 m0, s39
	s_nop 0
	global_load_lds_dwordx4 v[226:227], off
	s_waitcnt vmcnt(8)
	s_waitcnt lgkmcnt(0)
	v_mfma_f32_16x16x32_bf16 v[64:67], v[156:159], v[192:195], v[64:67]
	v_mfma_f32_16x16x32_bf16 v[60:63], v[164:167], v[192:195], v[60:63]
	v_mfma_f32_16x16x32_bf16 v[48:51], v[156:159], v[202:205], v[48:51]
	v_mfma_f32_16x16x32_bf16 v[44:47], v[164:167], v[202:205], v[44:47]
	s_barrier
	s_setprio 1
	s_waitcnt lgkmcnt(0)
	v_mfma_f32_16x16x32_bf16 v[32:35], v[156:159], v[210:213], v[32:35]
	v_mfma_f32_16x16x32_bf16 v[28:31], v[164:167], v[210:213], v[28:31]
	v_mfma_f32_16x16x32_bf16 v[16:19], v[156:159], v[218:221], v[16:19]
	v_mfma_f32_16x16x32_bf16 v[12:15], v[164:167], v[218:221], v[12:15]
	v_mfma_f32_16x16x32_bf16 v[64:67], v[160:163], v[198:201], v[64:67]
	v_mfma_f32_16x16x32_bf16 v[60:63], v[172:175], v[198:201], v[60:63]
	v_mfma_f32_16x16x32_bf16 v[48:51], v[160:163], v[206:209], v[48:51]
	v_mfma_f32_16x16x32_bf16 v[44:47], v[172:175], v[206:209], v[44:47]
	v_mfma_f32_16x16x32_bf16 v[32:35], v[160:163], v[214:217], v[32:35]
	v_mfma_f32_16x16x32_bf16 v[28:31], v[172:175], v[214:217], v[28:31]
	v_mfma_f32_16x16x32_bf16 v[16:19], v[160:163], v[222:225], v[16:19]
	v_mfma_f32_16x16x32_bf16 v[12:15], v[172:175], v[222:225], v[12:15]
	s_setprio 0
	s_setprio 1
	v_mfma_f32_16x16x32_bf16 v[56:59], v[176:179], v[192:195], v[56:59]
	v_mfma_f32_16x16x32_bf16 v[52:55], v[184:187], v[192:195], v[52:55]
	v_mfma_f32_16x16x32_bf16 v[40:43], v[176:179], v[202:205], v[40:43]
	v_mfma_f32_16x16x32_bf16 v[36:39], v[184:187], v[202:205], v[36:39]
	v_mfma_f32_16x16x32_bf16 v[24:27], v[176:179], v[210:213], v[24:27]
	v_mfma_f32_16x16x32_bf16 v[20:23], v[184:187], v[210:213], v[20:23]
	v_mfma_f32_16x16x32_bf16 v[8:11], v[176:179], v[218:221], v[8:11]
	v_mfma_f32_16x16x32_bf16 v[4:7], v[184:187], v[218:221], v[4:7]
	v_mfma_f32_16x16x32_bf16 v[56:59], v[180:183], v[198:201], v[56:59]
	v_mfma_f32_16x16x32_bf16 v[52:55], v[188:191], v[198:201], v[52:55]
	v_mfma_f32_16x16x32_bf16 v[40:43], v[180:183], v[206:209], v[40:43]
	v_mfma_f32_16x16x32_bf16 v[36:39], v[188:191], v[206:209], v[36:39]
	v_mfma_f32_16x16x32_bf16 v[24:27], v[180:183], v[214:217], v[24:27]
	v_mfma_f32_16x16x32_bf16 v[20:23], v[188:191], v[214:217], v[20:23]
	v_mfma_f32_16x16x32_bf16 v[8:11], v[180:183], v[222:225], v[8:11]
	v_mfma_f32_16x16x32_bf16 v[4:7], v[188:191], v[222:225], v[4:7]
	s_setprio 0
	s_barrier
	s_add_i32 s47, s47, 2
	s_add_u32 s22, s22, 0x100
	s_addc_u32 s23, s23, 0
	s_cmp_gt_u32 s47, 41
	s_cbranch_scc0 .LBB0_187
	s_add_u32 s2, s45, 0xffffff00
	s_addc_u32 s3, s46, -1
	s_and_b64 vcc, exec, s[6:7]
	s_cbranch_vccnz .LBB0_190
	v_mov_b32_e32 v4, 0
	s_mov_b32 s60, s42
	s_mov_b32 s25, s43
	s_mov_b64 s[12:13], s[20:21]
	s_mov_b32 s37, s44
	v_mov_b32_e32 v5, v4
	v_mov_b32_e32 v6, v4
	v_mov_b32_e32 v7, v4
	v_mov_b32_e32 v8, v4
	v_mov_b32_e32 v9, v4
	v_mov_b32_e32 v10, v4
	v_mov_b32_e32 v11, v4
	v_mov_b32_e32 v20, v4
	v_mov_b32_e32 v21, v4
	v_mov_b32_e32 v22, v4
	v_mov_b32_e32 v23, v4
	v_mov_b32_e32 v24, v4
	v_mov_b32_e32 v25, v4
	v_mov_b32_e32 v26, v4
	v_mov_b32_e32 v27, v4
	v_mov_b32_e32 v36, v4
	v_mov_b32_e32 v37, v4
	v_mov_b32_e32 v38, v4
	v_mov_b32_e32 v39, v4
	v_mov_b32_e32 v40, v4
	v_mov_b32_e32 v41, v4
	v_mov_b32_e32 v42, v4
	v_mov_b32_e32 v43, v4
	v_mov_b32_e32 v52, v4
	v_mov_b32_e32 v53, v4
	v_mov_b32_e32 v54, v4
	v_mov_b32_e32 v55, v4
	v_mov_b32_e32 v56, v4
	v_mov_b32_e32 v57, v4
	v_mov_b32_e32 v58, v4
	v_mov_b32_e32 v59, v4
	v_mov_b32_e32 v12, v4
	v_mov_b32_e32 v13, v4
	v_mov_b32_e32 v14, v4
	v_mov_b32_e32 v15, v4
	v_mov_b32_e32 v16, v4
	v_mov_b32_e32 v17, v4
	v_mov_b32_e32 v18, v4
	v_mov_b32_e32 v19, v4
	v_mov_b32_e32 v28, v4
	v_mov_b32_e32 v29, v4
	v_mov_b32_e32 v30, v4
	v_mov_b32_e32 v31, v4
	v_mov_b32_e32 v32, v4
	v_mov_b32_e32 v33, v4
	v_mov_b32_e32 v34, v4
	v_mov_b32_e32 v35, v4
	v_mov_b32_e32 v44, v4
	v_mov_b32_e32 v45, v4
	v_mov_b32_e32 v46, v4
	v_mov_b32_e32 v47, v4
	v_mov_b32_e32 v48, v4
	v_mov_b32_e32 v49, v4
	v_mov_b32_e32 v50, v4
	v_mov_b32_e32 v51, v4
	v_mov_b32_e32 v60, v4
	v_mov_b32_e32 v61, v4
	v_mov_b32_e32 v62, v4
	v_mov_b32_e32 v63, v4
	v_mov_b32_e32 v64, v4
	v_mov_b32_e32 v65, v4
	v_mov_b32_e32 v66, v4
	v_mov_b32_e32 v67, v4
	v_mov_b32_e32 v76, v4
	v_mov_b32_e32 v77, v4
	v_mov_b32_e32 v78, v4
	v_mov_b32_e32 v79, v4
	v_mov_b32_e32 v88, v4
	v_mov_b32_e32 v89, v4
	v_mov_b32_e32 v90, v4
	v_mov_b32_e32 v91, v4
	v_mov_b32_e32 v72, v4
	v_mov_b32_e32 v73, v4
	v_mov_b32_e32 v74, v4
	v_mov_b32_e32 v75, v4
	v_mov_b32_e32 v84, v4
	v_mov_b32_e32 v85, v4
	v_mov_b32_e32 v86, v4
	v_mov_b32_e32 v87, v4
	v_mov_b32_e32 v68, v4
	v_mov_b32_e32 v69, v4
	v_mov_b32_e32 v70, v4
	v_mov_b32_e32 v71, v4
	v_mov_b32_e32 v80, v4
	v_mov_b32_e32 v81, v4
	v_mov_b32_e32 v82, v4
	v_mov_b32_e32 v83, v4
	v_mov_b32_e32 v92, v4
	v_mov_b32_e32 v93, v4
	v_mov_b32_e32 v94, v4
	v_mov_b32_e32 v95, v4
	v_mov_b32_e32 v108, v4
	v_mov_b32_e32 v109, v4
	v_mov_b32_e32 v110, v4
	v_mov_b32_e32 v111, v4
	v_mov_b32_e32 v120, v4
	v_mov_b32_e32 v121, v4
	v_mov_b32_e32 v122, v4
	v_mov_b32_e32 v123, v4
	v_mov_b32_e32 v104, v4
	v_mov_b32_e32 v105, v4
	v_mov_b32_e32 v106, v4
	v_mov_b32_e32 v107, v4
	v_mov_b32_e32 v116, v4
	v_mov_b32_e32 v117, v4
	v_mov_b32_e32 v118, v4
	v_mov_b32_e32 v119, v4
	v_mov_b32_e32 v100, v4
	v_mov_b32_e32 v101, v4
	v_mov_b32_e32 v102, v4
	v_mov_b32_e32 v103, v4
	v_mov_b32_e32 v128, v4
	v_mov_b32_e32 v129, v4
	v_mov_b32_e32 v130, v4
	v_mov_b32_e32 v131, v4
	v_mov_b32_e32 v96, v4
	v_mov_b32_e32 v97, v4
	v_mov_b32_e32 v98, v4
	v_mov_b32_e32 v99, v4
	v_mov_b32_e32 v124, v4
	v_mov_b32_e32 v125, v4
	v_mov_b32_e32 v126, v4
	v_mov_b32_e32 v127, v4
	v_mov_b32_e32 v112, v4
	v_mov_b32_e32 v113, v4
	v_mov_b32_e32 v114, v4
	v_mov_b32_e32 v115, v4
	s_andn2_b64 vcc, exec, s[4:5]
	s_cbranch_vccnz .LBB0_191
	s_branch .LBB0_192

; #define PG8_STAGE(bufoff, gbase, voff) do { _Pragma("unroll") for (int _i = 0; _i < 2; ++_i) \
;         __builtin_amdgcn_global_load_lds((const unsigned*)((const char*)(gbase) + (voff)[_i]), (PG8_LAS unsigned*)(lds + (bufoff) + ldsw + _i * 8192), 16, 0, 0); } while (0)
; #define PG8_LDA(dst, b, h) do { _Pragma("unroll") for (int m = 0; m < 4; ++m) _Pragma("unroll") for (int k = 0; k < 2; ++k) dst[m][k] = *(const PG8_LAS bf16x8*)(lds + PG8_SA(b, h) + aoff + m * 2048 + k * 1024); } while (0)
; #define PG8_LDB(dst, b, h) do { _Pragma("unroll") for (int n = 0; n < 2; ++n) _Pragma("unroll") for (int k = 0; k < 2; ++k) dst[n][k] = *(const PG8_LAS bf16x8*)(lds + PG8_SB(b, h) + boff + n * 2048 + k * 1024); } while (0)
; #define PG8_MMA(ai, bj, At, Bt) do { __builtin_amdgcn_s_setprio(1); _Pragma("unroll") for (int m = 0; m < 4; ++m) _Pragma("unroll") for (int n = 0; n < 2; ++n) _Pragma("unroll") for (int k = 0; k < 2; ++k) \
;         acc[ai][bj][m][n] = __builtin_amdgcn_mfma_f32_16x16x32_bf16(Bt[n][k], At[m][k], acc[ai][bj][m][n], 0, 0, 0); __builtin_amdgcn_s_setprio(0); } while (0)
; #define PG8_WAIT_V(n) asm volatile("s_waitcnt vmcnt(" #n ")" ::: "memory")
; #define PG8_BAR __builtin_amdgcn_s_barrier()
; template <class Epi, class Sched, bool ALIGN_EPI = false, bool SP2 = false>
; __device__ __forceinline__ void gemm_phase(PG8_LAS unsigned char* lds, const Gemm g, const Sched& S, const Epi& E) {
;     ...
;         for (int t = 0; t < nt; t += 2) {
;             const bool last = (t == nt - 2);
;             const char* a1 = cA + (size_t)(t + 1) * kstep;
;             const char* a2 = last ? nA : cA + (size_t)(t + 2) * kstep; const char* b2 = last ? nB : cB + (size_t)(t + 2) * kstep;
;             const char* a3 = a2 + kstep; const char* b3 = b2 + kstep;
;             if (last && has_next) S.a_ready(nxt);
;             if constexpr (SP2) {
;             PG8_LDB(B0, 0, 0); PG8_LDB(B1, 0, 1); PG8_SCHED; PG8_LDA(At, 0, 0); PG8_STAGE(PG8_SA(1, 1), a1 + hstep, voffA);
;             PG8_WAIT_V(8); PG8_WAIT_L(0); PG8_BAR; PG8_MMA(0, 0, At, B0); PG8_MMA(0, 1, At, B1); PG8_BAR; PG8_SCHED;
;             PG8_LDA(At, 0, 1); PG8_STAGE(PG8_SB(0, 0), b2, voffB); PG8_STAGE(PG8_SB(0, 1), b2 + hstep, voffB); PG8_STAGE(PG8_SA(0, 0), a2, voffA);
;             PG8_WAIT_V(8); PG8_WAIT_L(0); PG8_BAR; PG8_MMA(1, 0, At, B0); PG8_MMA(1, 1, At, B1); PG8_BAR; PG8_SCHED;
.LBB0_334:
	ds_read_b128 v[148:151], v164
	ds_read_b128 v[152:155], v164 offset:1024
	ds_read_b128 v[156:159], v164 offset:2048
	ds_read_b128 v[172:175], v164 offset:3072
	ds_read_b128 v[176:179], v165
	ds_read_b128 v[180:183], v165 offset:1024
	ds_read_b128 v[184:187], v165 offset:2048
	ds_read_b128 v[188:191], v165 offset:3072
	s_add_u32 s2, s10, 0xfffc0080
	s_addc_u32 s3, s11, -1
	s_cmp_eq_u32 s37, 12
	s_cselect_b32 s13, s7, s3
	s_cselect_b32 s12, s9, s2
	s_cselect_b32 s3, s14, s36
	s_cselect_b32 s2, s15, s29
	v_lshl_add_u64 v[160:161], s[10:11], 0, v[140:141]
	s_add_i32 m0, s17, 0xc000
	ds_read_b128 v[192:195], v166
	ds_read_b128 v[198:201], v166 offset:1024
	ds_read_b128 v[202:205], v166 offset:2048
	ds_read_b128 v[206:209], v166 offset:3072
	ds_read_b128 v[210:213], v166 offset:4096
	ds_read_b128 v[214:217], v166 offset:5120
	ds_read_b128 v[218:221], v166 offset:6144
	ds_read_b128 v[222:225], v166 offset:7168
	global_load_lds_dwordx4 v[160:161], off
	v_lshl_add_u64 v[160:161], s[10:11], 0, v[142:143]
	s_add_i32 m0, s17, 0xe000
	s_nop 0
	global_load_lds_dwordx4 v[160:161], off
	s_waitcnt vmcnt(8)
	s_waitcnt lgkmcnt(0)
	v_mfma_f32_16x16x32_bf16 v[126:129], v[148:151], v[192:195], v[126:129]
	v_mfma_f32_16x16x32_bf16 v[122:125], v[156:159], v[192:195], v[122:125]
	v_mfma_f32_16x16x32_bf16 v[110:113], v[148:151], v[202:205], v[110:113]
	v_mfma_f32_16x16x32_bf16 v[106:109], v[156:159], v[202:205], v[106:109]
	s_barrier
	s_setprio 1
	s_waitcnt lgkmcnt(0)
	v_mfma_f32_16x16x32_bf16 v[94:97], v[148:151], v[210:213], v[94:97]
	v_mfma_f32_16x16x32_bf16 v[90:93], v[156:159], v[210:213], v[90:93]
	v_mfma_f32_16x16x32_bf16 v[78:81], v[148:151], v[218:221], v[78:81]
	v_mfma_f32_16x16x32_bf16 v[74:77], v[156:159], v[218:221], v[74:77]
	v_mfma_f32_16x16x32_bf16 v[126:129], v[152:155], v[198:201], v[126:129]
	v_mfma_f32_16x16x32_bf16 v[122:125], v[172:175], v[198:201], v[122:125]
	v_mfma_f32_16x16x32_bf16 v[110:113], v[152:155], v[206:209], v[110:113]
	v_mfma_f32_16x16x32_bf16 v[106:109], v[172:175], v[206:209], v[106:109]
	v_mfma_f32_16x16x32_bf16 v[94:97], v[152:155], v[214:217], v[94:97]
	v_mfma_f32_16x16x32_bf16 v[90:93], v[172:175], v[214:217], v[90:93]
	v_mfma_f32_16x16x32_bf16 v[78:81], v[152:155], v[222:225], v[78:81]
	v_mfma_f32_16x16x32_bf16 v[74:77], v[172:175], v[222:225], v[74:77]
	s_setprio 0
	s_setprio 1
	v_mfma_f32_16x16x32_bf16 v[118:121], v[176:179], v[192:195], v[118:121]
	v_mfma_f32_16x16x32_bf16 v[114:117], v[184:187], v[192:195], v[114:117]
	v_mfma_f32_16x16x32_bf16 v[102:105], v[176:179], v[202:205], v[102:105]
	v_mfma_f32_16x16x32_bf16 v[98:101], v[184:187], v[202:205], v[98:101]
	v_mfma_f32_16x16x32_bf16 v[86:89], v[176:179], v[210:213], v[86:89]
	v_mfma_f32_16x16x32_bf16 v[82:85], v[184:187], v[210:213], v[82:85]
	v_mfma_f32_16x16x32_bf16 v[70:73], v[176:179], v[218:221], v[70:73]
	v_mfma_f32_16x16x32_bf16 v[66:69], v[184:187], v[218:221], v[66:69]
	v_mfma_f32_16x16x32_bf16 v[118:121], v[180:183], v[198:201], v[118:121]
	v_mfma_f32_16x16x32_bf16 v[114:117], v[188:191], v[198:201], v[114:117]
	v_mfma_f32_16x16x32_bf16 v[102:105], v[180:183], v[206:209], v[102:105]
	v_mfma_f32_16x16x32_bf16 v[98:101], v[188:191], v[206:209], v[98:101]
	v_mfma_f32_16x16x32_bf16 v[86:89], v[180:183], v[214:217], v[86:89]
	v_mfma_f32_16x16x32_bf16 v[82:85], v[188:191], v[214:217], v[82:85]
	v_mfma_f32_16x16x32_bf16 v[70:73], v[180:183], v[222:225], v[70:73]
	v_mfma_f32_16x16x32_bf16 v[66:69], v[188:191], v[222:225], v[66:69]
	s_setprio 0
	s_barrier
	s_add_i32 s38, s44, s16
	v_lshl_add_u64 v[160:161], s[2:3], 0, v[132:133]
	s_mov_b32 m0, s38
	ds_read_b128 v[192:195], v166 offset:16384
	ds_read_b128 v[198:201], v166 offset:17408
	ds_read_b128 v[202:205], v166 offset:18432
	ds_read_b128 v[206:209], v166 offset:19456
	ds_read_b128 v[210:213], v166 offset:20480
	ds_read_b128 v[214:217], v166 offset:21504
	ds_read_b128 v[218:221], v166 offset:22528
	ds_read_b128 v[222:225], v166 offset:23552
	global_load_lds_dwordx4 v[160:161], off
	s_add_i32 m0, s38, 0x2000
	s_add_u32 s38, s2, 0x40000
	v_lshl_add_u64 v[226:227], s[2:3], 0, v[136:137]
	s_addc_u32 s39, s3, 0
	s_add_i32 s40, s45, s16
	global_load_lds_dwordx4 v[226:227], off
	v_lshl_add_u64 v[228:229], s[38:39], 0, v[132:133]
	s_mov_b32 m0, s40
	v_lshl_add_u64 v[230:231], s[12:13], 0, v[134:135]
	global_load_lds_dwordx4 v[228:229], off
	v_lshl_add_u64 v[228:229], s[38:39], 0, v[136:137]
	s_add_i32 m0, s40, 0x2000
	s_nop 0
	global_load_lds_dwordx4 v[228:229], off
	v_lshl_add_u64 v[228:229], s[12:13], 0, v[130:131]
	s_mov_b32 m0, s17
	s_nop 0
	global_load_lds_dwordx4 v[228:229], off
	s_mov_b32 m0, s24
	s_nop 0
	global_load_lds_dwordx4 v[230:231], off
	s_waitcnt vmcnt(8)
	s_waitcnt lgkmcnt(0)
	v_mfma_f32_16x16x32_bf16 v[62:65], v[148:151], v[192:195], v[62:65]
	v_mfma_f32_16x16x32_bf16 v[58:61], v[156:159], v[192:195], v[58:61]
	v_mfma_f32_16x16x32_bf16 v[46:49], v[148:151], v[202:205], v[46:49]
	v_mfma_f32_16x16x32_bf16 v[42:45], v[156:159], v[202:205], v[42:45]
	s_barrier
; #define PG8_STAGE(bufoff, gbase, voff) do { _Pragma("unroll") for (int _i = 0; _i < 2; ++_i) \
;         __builtin_amdgcn_global_load_lds((const unsigned*)((const char*)(gbase) + (voff)[_i]), (PG8_LAS unsigned*)(lds + (bufoff) + ldsw + _i * 8192), 16, 0, 0); } while (0)
; #define PG8_LDA(dst, b, h) do { _Pragma("unroll") for (int m = 0; m < 4; ++m) _Pragma("unroll") for (int k = 0; k < 2; ++k) dst[m][k] = *(const PG8_LAS bf16x8*)(lds + PG8_SA(b, h) + aoff + m * 2048 + k * 1024); } while (0)
; #define PG8_LDB(dst, b, h) do { _Pragma("unroll") for (int n = 0; n < 2; ++n) _Pragma("unroll") for (int k = 0; k < 2; ++k) dst[n][k] = *(const PG8_LAS bf16x8*)(lds + PG8_SB(b, h) + boff + n * 2048 + k * 1024); } while (0)
; #define PG8_MMA(ai, bj, At, Bt) do { __builtin_amdgcn_s_setprio(1); _Pragma("unroll") for (int m = 0; m < 4; ++m) _Pragma("unroll") for (int n = 0; n < 2; ++n) _Pragma("unroll") for (int k = 0; k < 2; ++k) \
;         acc[ai][bj][m][n] = __builtin_amdgcn_mfma_f32_16x16x32_bf16(Bt[n][k], At[m][k], acc[ai][bj][m][n], 0, 0, 0); __builtin_amdgcn_s_setprio(0); } while (0)
; #define PG8_WAIT_V(n) asm volatile("s_waitcnt vmcnt(" #n ")" ::: "memory")
; #define PG8_WAIT_L(n) asm volatile("s_waitcnt lgkmcnt(" #n ")" ::: "memory")
; #define PG8_BAR __builtin_amdgcn_s_barrier()
; #define PG8_SCHED __builtin_amdgcn_sched_barrier(0)
; template <class Epi, class Sched, bool ALIGN_EPI = false, bool SP2 = false>
; __device__ __forceinline__ void gemm_phase(PG8_LAS unsigned char* lds, const Gemm g, const Sched& S, const Epi& E) {
;     ...
;             PG8_WAIT_V(8); PG8_WAIT_L(0); PG8_BAR; PG8_MMA(1, 0, At, B0); PG8_MMA(1, 1, At, B1); PG8_BAR; PG8_SCHED;
;             PG8_LDB(B0, 1, 0); PG8_LDB(B1, 1, 1); PG8_SCHED; PG8_LDA(At, 1, 0); PG8_STAGE(PG8_SA(0, 1), a2 + hstep, voffA);
;             PG8_WAIT_V(8); PG8_WAIT_L(0); PG8_BAR; PG8_MMA(0, 0, At, B0); PG8_MMA(0, 1, At, B1); PG8_BAR; PG8_SCHED;
	s_setprio 1
	s_waitcnt lgkmcnt(0)
	v_mfma_f32_16x16x32_bf16 v[30:33], v[148:151], v[210:213], v[30:33]
	v_mfma_f32_16x16x32_bf16 v[26:29], v[156:159], v[210:213], v[26:29]
	v_mfma_f32_16x16x32_bf16 v[14:17], v[148:151], v[218:221], v[14:17]
	v_mfma_f32_16x16x32_bf16 v[10:13], v[156:159], v[218:221], v[10:13]
	v_mfma_f32_16x16x32_bf16 v[62:65], v[152:155], v[198:201], v[62:65]
	v_mfma_f32_16x16x32_bf16 v[58:61], v[172:175], v[198:201], v[58:61]
	v_mfma_f32_16x16x32_bf16 v[46:49], v[152:155], v[206:209], v[46:49]
	v_mfma_f32_16x16x32_bf16 v[42:45], v[172:175], v[206:209], v[42:45]
	v_mfma_f32_16x16x32_bf16 v[30:33], v[152:155], v[214:217], v[30:33]
	v_mfma_f32_16x16x32_bf16 v[26:29], v[172:175], v[214:217], v[26:29]
	v_mfma_f32_16x16x32_bf16 v[14:17], v[152:155], v[222:225], v[14:17]
	v_mfma_f32_16x16x32_bf16 v[10:13], v[172:175], v[222:225], v[10:13]
	s_setprio 0
	s_setprio 1
	v_mfma_f32_16x16x32_bf16 v[54:57], v[176:179], v[192:195], v[54:57]
	v_mfma_f32_16x16x32_bf16 v[50:53], v[184:187], v[192:195], v[50:53]
	v_mfma_f32_16x16x32_bf16 v[38:41], v[176:179], v[202:205], v[38:41]
	v_mfma_f32_16x16x32_bf16 v[34:37], v[184:187], v[202:205], v[34:37]
	v_mfma_f32_16x16x32_bf16 v[22:25], v[176:179], v[210:213], v[22:25]
	v_mfma_f32_16x16x32_bf16 v[18:21], v[184:187], v[210:213], v[18:21]
	v_mfma_f32_16x16x32_bf16 v[6:9], v[176:179], v[218:221], v[6:9]
	v_mfma_f32_16x16x32_bf16 v[2:5], v[184:187], v[218:221], v[2:5]
	v_mfma_f32_16x16x32_bf16 v[54:57], v[180:183], v[198:201], v[54:57]
	v_mfma_f32_16x16x32_bf16 v[50:53], v[188:191], v[198:201], v[50:53]
	v_mfma_f32_16x16x32_bf16 v[38:41], v[180:183], v[206:209], v[38:41]
	v_mfma_f32_16x16x32_bf16 v[34:37], v[188:191], v[206:209], v[34:37]
	v_mfma_f32_16x16x32_bf16 v[22:25], v[180:183], v[214:217], v[22:25]
	v_mfma_f32_16x16x32_bf16 v[18:21], v[188:191], v[214:217], v[18:21]
	v_mfma_f32_16x16x32_bf16 v[6:9], v[180:183], v[222:225], v[6:9]
	v_mfma_f32_16x16x32_bf16 v[2:5], v[188:191], v[222:225], v[2:5]
	s_setprio 0
	s_barrier
	s_add_i32 s38, 0, 0x18000
	v_add_u32_e32 v138, s38, v162
	s_add_i32 s39, 0, 0x1c000
	ds_read_b128 v[148:151], v138
	ds_read_b128 v[152:155], v138 offset:1024
	ds_read_b128 v[156:159], v138 offset:2048
	ds_read_b128 v[172:175], v138 offset:3072
	v_add_u32_e32 v138, s39, v162
	ds_read_b128 v[176:179], v138
	ds_read_b128 v[180:183], v138 offset:1024
	ds_read_b128 v[184:187], v138 offset:2048
	ds_read_b128 v[188:191], v138 offset:3072
	s_add_u32 s12, s12, 0x40000
	s_addc_u32 s13, s13, 0
	s_mov_b32 m0, s25
	v_lshl_add_u64 v[232:233], s[12:13], 0, v[130:131]
	ds_read_b128 v[192:195], v166 offset:32768
	ds_read_b128 v[198:201], v166 offset:33792
	ds_read_b128 v[202:205], v166 offset:34816
	ds_read_b128 v[206:209], v166 offset:35840
	ds_read_b128 v[210:213], v166 offset:36864
	ds_read_b128 v[214:217], v166 offset:37888
	ds_read_b128 v[218:221], v166 offset:38912
	ds_read_b128 v[222:225], v166 offset:39936
	global_load_lds_dwordx4 v[232:233], off
	v_lshl_add_u64 v[232:233], s[12:13], 0, v[134:135]
	s_mov_b32 m0, s26
	s_nop 0
	global_load_lds_dwordx4 v[232:233], off
	s_waitcnt vmcnt(8)
	s_waitcnt lgkmcnt(0)
	v_mfma_f32_16x16x32_bf16 v[126:129], v[148:151], v[192:195], v[126:129]
	v_mfma_f32_16x16x32_bf16 v[122:125], v[156:159], v[192:195], v[122:125]
	v_mfma_f32_16x16x32_bf16 v[110:113], v[148:151], v[202:205], v[110:113]
	v_mfma_f32_16x16x32_bf16 v[106:109], v[156:159], v[202:205], v[106:109]
	s_barrier
	s_setprio 1
	s_waitcnt lgkmcnt(0)
	v_mfma_f32_16x16x32_bf16 v[94:97], v[148:151], v[210:213], v[94:97]
	v_mfma_f32_16x16x32_bf16 v[90:93], v[156:159], v[210:213], v[90:93]
	v_mfma_f32_16x16x32_bf16 v[78:81], v[148:151], v[218:221], v[78:81]
	v_mfma_f32_16x16x32_bf16 v[74:77], v[156:159], v[218:221], v[74:77]
	v_mfma_f32_16x16x32_bf16 v[126:129], v[152:155], v[198:201], v[126:129]
	v_mfma_f32_16x16x32_bf16 v[122:125], v[172:175], v[198:201], v[122:125]
	v_mfma_f32_16x16x32_bf16 v[110:113], v[152:155], v[206:209], v[110:113]
	v_mfma_f32_16x16x32_bf16 v[106:109], v[172:175], v[206:209], v[106:109]
	v_mfma_f32_16x16x32_bf16 v[94:97], v[152:155], v[214:217], v[94:97]
	v_mfma_f32_16x16x32_bf16 v[90:93], v[172:175], v[214:217], v[90:93]
	v_mfma_f32_16x16x32_bf16 v[78:81], v[152:155], v[222:225], v[78:81]
	v_mfma_f32_16x16x32_bf16 v[74:77], v[172:175], v[222:225], v[74:77]
	s_setprio 0
	s_setprio 1
	v_mfma_f32_16x16x32_bf16 v[118:121], v[176:179], v[192:195], v[118:121]
	v_mfma_f32_16x16x32_bf16 v[114:117], v[184:187], v[192:195], v[114:117]
	v_mfma_f32_16x16x32_bf16 v[102:105], v[176:179], v[202:205], v[102:105]
	v_mfma_f32_16x16x32_bf16 v[98:101], v[184:187], v[202:205], v[98:101]
	v_mfma_f32_16x16x32_bf16 v[86:89], v[176:179], v[210:213], v[86:89]
	v_mfma_f32_16x16x32_bf16 v[82:85], v[184:187], v[210:213], v[82:85]
	v_mfma_f32_16x16x32_bf16 v[70:73], v[176:179], v[218:221], v[70:73]
	v_mfma_f32_16x16x32_bf16 v[66:69], v[184:187], v[218:221], v[66:69]
	v_mfma_f32_16x16x32_bf16 v[118:121], v[180:183], v[198:201], v[118:121]
	v_mfma_f32_16x16x32_bf16 v[114:117], v[188:191], v[198:201], v[114:117]
	v_mfma_f32_16x16x32_bf16 v[102:105], v[180:183], v[206:209], v[102:105]
	v_mfma_f32_16x16x32_bf16 v[98:101], v[188:191], v[206:209], v[98:101]
	v_mfma_f32_16x16x32_bf16 v[86:89], v[180:183], v[214:217], v[86:89]
	v_mfma_f32_16x16x32_bf16 v[82:85], v[188:191], v[214:217], v[82:85]
	v_mfma_f32_16x16x32_bf16 v[70:73], v[180:183], v[222:225], v[70:73]
	v_mfma_f32_16x16x32_bf16 v[66:69], v[188:191], v[222:225], v[66:69]
	s_setprio 0
	s_barrier
; #define PG8_STAGE(bufoff, gbase, voff) do { _Pragma("unroll") for (int _i = 0; _i < 2; ++_i) \
;         __builtin_amdgcn_global_load_lds((const unsigned*)((const char*)(gbase) + (voff)[_i]), (PG8_LAS unsigned*)(lds + (bufoff) + ldsw + _i * 8192), 16, 0, 0); } while (0)
; #define PG8_LDA(dst, b, h) do { _Pragma("unroll") for (int m = 0; m < 4; ++m) _Pragma("unroll") for (int k = 0; k < 2; ++k) dst[m][k] = *(const PG8_LAS bf16x8*)(lds + PG8_SA(b, h) + aoff + m * 2048 + k * 1024); } while (0)
; #define PG8_MMA(ai, bj, At, Bt) do { __builtin_amdgcn_s_setprio(1); _Pragma("unroll") for (int m = 0; m < 4; ++m) _Pragma("unroll") for (int n = 0; n < 2; ++n) _Pragma("unroll") for (int k = 0; k < 2; ++k) \
;         acc[ai][bj][m][n] = __builtin_amdgcn_mfma_f32_16x16x32_bf16(Bt[n][k], At[m][k], acc[ai][bj][m][n], 0, 0, 0); __builtin_amdgcn_s_setprio(0); } while (0)
; #define PG8_WAIT_V(n) asm volatile("s_waitcnt vmcnt(" #n ")" ::: "memory")
; #define PG8_WAIT_L(n) asm volatile("s_waitcnt lgkmcnt(" #n ")" ::: "memory")
; #define PG8_BAR __builtin_amdgcn_s_barrier()
; #define PG8_SCHED __builtin_amdgcn_sched_barrier(0)
; template <class Epi, class Sched, bool ALIGN_EPI = false, bool SP2 = false>
; __device__ __forceinline__ void gemm_phase(PG8_LAS unsigned char* lds, const Gemm g, const Sched& S, const Epi& E) {
;     ...
;             PG8_LDA(At, 1, 1); PG8_STAGE(PG8_SB(1, 0), b3, voffB); PG8_STAGE(PG8_SB(1, 1), b3 + hstep, voffB); PG8_STAGE(PG8_SA(1, 0), a3, voffA);
;             PG8_WAIT_V(8); PG8_WAIT_L(0); PG8_BAR; PG8_MMA(1, 0, At, B0); PG8_MMA(1, 1, At, B1); PG8_BAR; PG8_SCHED;
;     ...
;         if constexpr (ALIGN_EPI) { if (wr == 0) PG8_BAR; }
	s_add_i32 s12, s38, s16
	v_lshl_add_u64 v[160:161], v[160:161], 0, s[20:21]
	s_mov_b32 m0, s12
	ds_read_b128 v[192:195], v166 offset:49152
	ds_read_b128 v[198:201], v166 offset:50176
	ds_read_b128 v[202:205], v166 offset:51200
	ds_read_b128 v[206:209], v166 offset:52224
	ds_read_b128 v[210:213], v166 offset:53248
	ds_read_b128 v[214:217], v166 offset:54272
	ds_read_b128 v[218:221], v166 offset:55296
	ds_read_b128 v[222:225], v166 offset:56320
	global_load_lds_dwordx4 v[160:161], off
	s_add_i32 m0, s12, 0x2000
	s_add_u32 s2, s2, 0x40080
	v_lshl_add_u64 v[160:161], v[226:227], 0, s[20:21]
	s_addc_u32 s3, s3, 0
	s_add_i32 s12, s39, s16
	global_load_lds_dwordx4 v[160:161], off
	v_lshl_add_u64 v[160:161], s[2:3], 0, v[132:133]
	s_mov_b32 m0, s12
	s_nop 0
	global_load_lds_dwordx4 v[160:161], off
	v_lshl_add_u64 v[160:161], s[2:3], 0, v[136:137]
	s_add_i32 m0, s12, 0x2000
	s_nop 0
	global_load_lds_dwordx4 v[160:161], off
	v_lshl_add_u64 v[160:161], v[228:229], 0, s[20:21]
	s_mov_b32 m0, s34
	s_nop 0
	global_load_lds_dwordx4 v[160:161], off
	v_lshl_add_u64 v[160:161], v[230:231], 0, s[20:21]
	s_mov_b32 m0, s35
	s_nop 0
	global_load_lds_dwordx4 v[160:161], off
	s_waitcnt vmcnt(8)
	s_waitcnt lgkmcnt(0)
	v_mfma_f32_16x16x32_bf16 v[62:65], v[148:151], v[192:195], v[62:65]
	v_mfma_f32_16x16x32_bf16 v[58:61], v[156:159], v[192:195], v[58:61]
	v_mfma_f32_16x16x32_bf16 v[46:49], v[148:151], v[202:205], v[46:49]
	v_mfma_f32_16x16x32_bf16 v[42:45], v[156:159], v[202:205], v[42:45]
	s_barrier
	s_setprio 1
	s_waitcnt lgkmcnt(0)
	v_mfma_f32_16x16x32_bf16 v[30:33], v[148:151], v[210:213], v[30:33]
	v_mfma_f32_16x16x32_bf16 v[26:29], v[156:159], v[210:213], v[26:29]
	v_mfma_f32_16x16x32_bf16 v[14:17], v[148:151], v[218:221], v[14:17]
	v_mfma_f32_16x16x32_bf16 v[10:13], v[156:159], v[218:221], v[10:13]
	v_mfma_f32_16x16x32_bf16 v[62:65], v[152:155], v[198:201], v[62:65]
	v_mfma_f32_16x16x32_bf16 v[58:61], v[172:175], v[198:201], v[58:61]
	v_mfma_f32_16x16x32_bf16 v[46:49], v[152:155], v[206:209], v[46:49]
	v_mfma_f32_16x16x32_bf16 v[42:45], v[172:175], v[206:209], v[42:45]
	v_mfma_f32_16x16x32_bf16 v[30:33], v[152:155], v[214:217], v[30:33]
	v_mfma_f32_16x16x32_bf16 v[26:29], v[172:175], v[214:217], v[26:29]
	v_mfma_f32_16x16x32_bf16 v[14:17], v[152:155], v[222:225], v[14:17]
	v_mfma_f32_16x16x32_bf16 v[10:13], v[172:175], v[222:225], v[10:13]
	s_setprio 0
	s_setprio 1
	v_mfma_f32_16x16x32_bf16 v[54:57], v[176:179], v[192:195], v[54:57]
	v_mfma_f32_16x16x32_bf16 v[50:53], v[184:187], v[192:195], v[50:53]
	v_mfma_f32_16x16x32_bf16 v[38:41], v[176:179], v[202:205], v[38:41]
	v_mfma_f32_16x16x32_bf16 v[34:37], v[184:187], v[202:205], v[34:37]
	v_mfma_f32_16x16x32_bf16 v[22:25], v[176:179], v[210:213], v[22:25]
	v_mfma_f32_16x16x32_bf16 v[18:21], v[184:187], v[210:213], v[18:21]
	v_mfma_f32_16x16x32_bf16 v[6:9], v[176:179], v[218:221], v[6:9]
	v_mfma_f32_16x16x32_bf16 v[2:5], v[184:187], v[218:221], v[2:5]
	v_mfma_f32_16x16x32_bf16 v[54:57], v[180:183], v[198:201], v[54:57]
	v_mfma_f32_16x16x32_bf16 v[50:53], v[188:191], v[198:201], v[50:53]
	v_mfma_f32_16x16x32_bf16 v[38:41], v[180:183], v[206:209], v[38:41]
	v_mfma_f32_16x16x32_bf16 v[34:37], v[188:191], v[206:209], v[34:37]
	v_mfma_f32_16x16x32_bf16 v[22:25], v[180:183], v[214:217], v[22:25]
	v_mfma_f32_16x16x32_bf16 v[18:21], v[188:191], v[214:217], v[18:21]
	v_mfma_f32_16x16x32_bf16 v[6:9], v[180:183], v[222:225], v[6:9]
	v_mfma_f32_16x16x32_bf16 v[2:5], v[188:191], v[222:225], v[2:5]
	s_setprio 0
	s_barrier
	s_add_i32 s37, s37, 2
	s_add_u32 s10, s10, 0x100
	s_addc_u32 s11, s11, 0
	s_add_u32 s29, s29, 0x100
	s_addc_u32 s36, s36, 0
	s_cmp_gt_u32 s37, 13
	s_cbranch_scc0 .LBB0_334
	s_and_b64 vcc, exec, s[22:23]
	s_cbranch_vccz .LBB0_337
	s_barrier

; #define PG8_STAGE(bufoff, gbase, voff) do { _Pragma("unroll") for (int _i = 0; _i < 2; ++_i) \
;         __builtin_amdgcn_global_load_lds((const unsigned*)((const char*)(gbase) + (voff)[_i]), (PG8_LAS unsigned*)(lds + (bufoff) + ldsw + _i * 8192), 16, 0, 0); } while (0)
; #define PG8_LDA(dst, b, h) do { _Pragma("unroll") for (int m = 0; m < 4; ++m) _Pragma("unroll") for (int k = 0; k < 2; ++k) dst[m][k] = *(const PG8_LAS bf16x8*)(lds + PG8_SA(b, h) + aoff + m * 2048 + k * 1024); } while (0)
; #define PG8_LDB(dst, b, h) do { _Pragma("unroll") for (int n = 0; n < 2; ++n) _Pragma("unroll") for (int k = 0; k < 2; ++k) dst[n][k] = *(const PG8_LAS bf16x8*)(lds + PG8_SB(b, h) + boff + n * 2048 + k * 1024); } while (0)
; #define PG8_MMA(ai, bj, At, Bt) do { __builtin_amdgcn_s_setprio(1); _Pragma("unroll") for (int m = 0; m < 4; ++m) _Pragma("unroll") for (int n = 0; n < 2; ++n) _Pragma("unroll") for (int k = 0; k < 2; ++k) \
;         acc[ai][bj][m][n] = __builtin_amdgcn_mfma_f32_16x16x32_bf16(Bt[n][k], At[m][k], acc[ai][bj][m][n], 0, 0, 0); __builtin_amdgcn_s_setprio(0); } while (0)
; #define PG8_WAIT_V(n) asm volatile("s_waitcnt vmcnt(" #n ")" ::: "memory")
; #define PG8_BAR __builtin_amdgcn_s_barrier()
; template <class Epi, class Sched, bool ALIGN_EPI = false, bool SP2 = false>
; __device__ __forceinline__ void gemm_phase(PG8_LAS unsigned char* lds, const Gemm g, const Sched& S, const Epi& E) {
;     ...
;         for (int t = 0; t < nt; t += 2) {
;             const bool last = (t == nt - 2);
;             const char* a1 = cA + (size_t)(t + 1) * kstep;
;             const char* a2 = last ? nA : cA + (size_t)(t + 2) * kstep; const char* b2 = last ? nB : cB + (size_t)(t + 2) * kstep;
;             const char* a3 = a2 + kstep; const char* b3 = b2 + kstep;
;             if (last && has_next) S.a_ready(nxt);
;             if constexpr (SP2) {
;             PG8_LDB(B0, 0, 0); PG8_LDB(B1, 0, 1); PG8_SCHED; PG8_LDA(At, 0, 0); PG8_STAGE(PG8_SA(1, 1), a1 + hstep, voffA);
;             PG8_WAIT_V(8); PG8_WAIT_L(0); PG8_BAR; PG8_MMA(0, 0, At, B0); PG8_MMA(0, 1, At, B1); PG8_BAR; PG8_SCHED;
;             PG8_LDA(At, 0, 1); PG8_STAGE(PG8_SB(0, 0), b2, voffB); PG8_STAGE(PG8_SB(0, 1), b2 + hstep, voffB); PG8_STAGE(PG8_SA(0, 0), a2, voffA);
;             PG8_WAIT_V(8); PG8_WAIT_L(0); PG8_BAR; PG8_MMA(1, 0, At, B0); PG8_MMA(1, 1, At, B1); PG8_BAR; PG8_SCHED;
.LBB0_1488:
	v_add_u32_e32 v162, s43, v152
	ds_read_b128 v[154:157], v162
	ds_read_b128 v[158:161], v162 offset:1024
	ds_read_b128 v[166:169], v162 offset:2048
	ds_read_b128 v[170:173], v162 offset:3072
	v_add_u32_e32 v162, s44, v152
	s_add_u32 s2, s0, s40
	ds_read_b128 v[174:177], v162
	ds_read_b128 v[178:181], v162 offset:1024
	ds_read_b128 v[182:185], v162 offset:2048
	ds_read_b128 v[186:189], v162 offset:3072
	s_addc_u32 s3, s1, s41
	s_add_u32 s2, s2, 0x100
	s_addc_u32 s3, s3, 0
	s_add_u32 s51, s46, s40
	s_addc_u32 s52, s47, s41
	s_cmpk_eq_i32 s40, 0x700
	s_cselect_b32 s15, s29, s3
	s_cselect_b32 s14, s48, s2
	s_cselect_b32 s3, s25, s52
	s_cselect_b32 s2, s49, s51
	v_lshl_add_u64 v[162:163], v[146:147], 0, s[40:41]
	s_add_i32 m0, s26, 0xc000
	ds_read_b128 v[190:193], v153
	ds_read_b128 v[194:197], v153 offset:1024
	ds_read_b128 v[198:201], v153 offset:2048
	ds_read_b128 v[202:205], v153 offset:3072
	ds_read_b128 v[206:209], v153 offset:4096
	ds_read_b128 v[210:213], v153 offset:5120
	ds_read_b128 v[214:217], v153 offset:6144
	ds_read_b128 v[218:221], v153 offset:7168
	global_load_lds_dwordx4 v[162:163], off
	v_lshl_add_u64 v[162:163], v[148:149], 0, s[40:41]
	s_add_i32 m0, s26, 0xe000
	s_nop 0
	global_load_lds_dwordx4 v[162:163], off
	s_waitcnt vmcnt(8)
	s_waitcnt lgkmcnt(0)
	v_mfma_f32_16x16x32_bf16 v[94:97], v[154:157], v[190:193], v[94:97]
	v_mfma_f32_16x16x32_bf16 v[102:105], v[166:169], v[190:193], v[102:105]
	v_mfma_f32_16x16x32_bf16 v[106:109], v[154:157], v[198:201], v[106:109]
	v_mfma_f32_16x16x32_bf16 v[110:113], v[166:169], v[198:201], v[110:113]
	s_barrier
	s_setprio 1
	s_waitcnt lgkmcnt(0)
	v_mfma_f32_16x16x32_bf16 v[114:117], v[154:157], v[206:209], v[114:117]
	v_mfma_f32_16x16x32_bf16 v[122:125], v[166:169], v[206:209], v[122:125]
	v_mfma_f32_16x16x32_bf16 v[126:129], v[154:157], v[214:217], v[126:129]
	v_mfma_f32_16x16x32_bf16 v[118:121], v[166:169], v[214:217], v[118:121]
	v_mfma_f32_16x16x32_bf16 v[94:97], v[158:161], v[194:197], v[94:97]
	v_mfma_f32_16x16x32_bf16 v[102:105], v[170:173], v[194:197], v[102:105]
	v_mfma_f32_16x16x32_bf16 v[106:109], v[158:161], v[202:205], v[106:109]
	v_mfma_f32_16x16x32_bf16 v[110:113], v[170:173], v[202:205], v[110:113]
	v_mfma_f32_16x16x32_bf16 v[114:117], v[158:161], v[210:213], v[114:117]
	v_mfma_f32_16x16x32_bf16 v[122:125], v[170:173], v[210:213], v[122:125]
	v_mfma_f32_16x16x32_bf16 v[126:129], v[158:161], v[218:221], v[126:129]
	v_mfma_f32_16x16x32_bf16 v[118:121], v[170:173], v[218:221], v[118:121]
	s_setprio 0
	s_setprio 1
	v_mfma_f32_16x16x32_bf16 v[90:93], v[174:177], v[190:193], v[90:93]
	v_mfma_f32_16x16x32_bf16 v[74:77], v[182:185], v[190:193], v[74:77]
	v_mfma_f32_16x16x32_bf16 v[78:81], v[174:177], v[198:201], v[78:81]
	v_mfma_f32_16x16x32_bf16 v[66:69], v[182:185], v[198:201], v[66:69]
	v_mfma_f32_16x16x32_bf16 v[98:101], v[174:177], v[206:209], v[98:101]
	v_mfma_f32_16x16x32_bf16 v[86:89], v[182:185], v[206:209], v[86:89]
	v_mfma_f32_16x16x32_bf16 v[82:85], v[174:177], v[214:217], v[82:85]
	v_mfma_f32_16x16x32_bf16 v[70:73], v[182:185], v[214:217], v[70:73]
	v_mfma_f32_16x16x32_bf16 v[90:93], v[178:181], v[194:197], v[90:93]
	v_mfma_f32_16x16x32_bf16 v[74:77], v[186:189], v[194:197], v[74:77]
	v_mfma_f32_16x16x32_bf16 v[78:81], v[178:181], v[202:205], v[78:81]
	v_mfma_f32_16x16x32_bf16 v[66:69], v[186:189], v[202:205], v[66:69]
	v_mfma_f32_16x16x32_bf16 v[98:101], v[178:181], v[210:213], v[98:101]
	v_mfma_f32_16x16x32_bf16 v[86:89], v[186:189], v[210:213], v[86:89]
	v_mfma_f32_16x16x32_bf16 v[82:85], v[178:181], v[218:221], v[82:85]
	v_mfma_f32_16x16x32_bf16 v[70:73], v[186:189], v[218:221], v[70:73]
	s_setprio 0
	s_barrier
	s_add_i32 s51, s43, s21
	v_lshl_add_u64 v[162:163], s[2:3], 0, v[132:133]
	s_mov_b32 m0, s51
	ds_read_b128 v[190:193], v153 offset:16384
	ds_read_b128 v[194:197], v153 offset:17408
	ds_read_b128 v[198:201], v153 offset:18432
	ds_read_b128 v[202:205], v153 offset:19456
	ds_read_b128 v[206:209], v153 offset:20480
	ds_read_b128 v[210:213], v153 offset:21504
	ds_read_b128 v[214:217], v153 offset:22528
	ds_read_b128 v[218:221], v153 offset:23552
	global_load_lds_dwordx4 v[162:163], off
	s_add_i32 m0, s51, 0x2000
	s_add_u32 s52, s2, 0x40000
	v_lshl_add_u64 v[222:223], s[2:3], 0, v[136:137]
	s_addc_u32 s53, s3, 0
	s_add_i32 s51, s44, s21
	global_load_lds_dwordx4 v[222:223], off
	v_lshl_add_u64 v[224:225], s[52:53], 0, v[132:133]
	s_mov_b32 m0, s51
	v_lshl_add_u64 v[226:227], s[14:15], 0, v[134:135]
	global_load_lds_dwordx4 v[224:225], off
	v_lshl_add_u64 v[224:225], s[52:53], 0, v[136:137]
	s_add_i32 m0, s51, 0x2000
	s_nop 0
	global_load_lds_dwordx4 v[224:225], off
	v_lshl_add_u64 v[224:225], s[14:15], 0, v[130:131]
	s_mov_b32 m0, s26
	s_nop 0
	global_load_lds_dwordx4 v[224:225], off
	s_mov_b32 m0, s27
	s_nop 0
	global_load_lds_dwordx4 v[226:227], off
	s_waitcnt vmcnt(8)
	s_waitcnt lgkmcnt(0)
	v_mfma_f32_16x16x32_bf16 v[62:65], v[154:157], v[190:193], v[62:65]
	v_mfma_f32_16x16x32_bf16 v[58:61], v[166:169], v[190:193], v[58:61]
	v_mfma_f32_16x16x32_bf16 v[46:49], v[154:157], v[198:201], v[46:49]
	v_mfma_f32_16x16x32_bf16 v[42:45], v[166:169], v[198:201], v[42:45]
	s_barrier
; #define PG8_STAGE(bufoff, gbase, voff) do { _Pragma("unroll") for (int _i = 0; _i < 2; ++_i) \
;         __builtin_amdgcn_global_load_lds((const unsigned*)((const char*)(gbase) + (voff)[_i]), (PG8_LAS unsigned*)(lds + (bufoff) + ldsw + _i * 8192), 16, 0, 0); } while (0)
; #define PG8_LDA(dst, b, h) do { _Pragma("unroll") for (int m = 0; m < 4; ++m) _Pragma("unroll") for (int k = 0; k < 2; ++k) dst[m][k] = *(const PG8_LAS bf16x8*)(lds + PG8_SA(b, h) + aoff + m * 2048 + k * 1024); } while (0)
; #define PG8_LDB(dst, b, h) do { _Pragma("unroll") for (int n = 0; n < 2; ++n) _Pragma("unroll") for (int k = 0; k < 2; ++k) dst[n][k] = *(const PG8_LAS bf16x8*)(lds + PG8_SB(b, h) + boff + n * 2048 + k * 1024); } while (0)
; #define PG8_MMA(ai, bj, At, Bt) do { __builtin_amdgcn_s_setprio(1); _Pragma("unroll") for (int m = 0; m < 4; ++m) _Pragma("unroll") for (int n = 0; n < 2; ++n) _Pragma("unroll") for (int k = 0; k < 2; ++k) \
;         acc[ai][bj][m][n] = __builtin_amdgcn_mfma_f32_16x16x32_bf16(Bt[n][k], At[m][k], acc[ai][bj][m][n], 0, 0, 0); __builtin_amdgcn_s_setprio(0); } while (0)
; #define PG8_WAIT_V(n) asm volatile("s_waitcnt vmcnt(" #n ")" ::: "memory")
; #define PG8_WAIT_L(n) asm volatile("s_waitcnt lgkmcnt(" #n ")" ::: "memory")
; #define PG8_BAR __builtin_amdgcn_s_barrier()
; #define PG8_SCHED __builtin_amdgcn_sched_barrier(0)
; template <class Epi, class Sched, bool ALIGN_EPI = false, bool SP2 = false>
; __device__ __forceinline__ void gemm_phase(PG8_LAS unsigned char* lds, const Gemm g, const Sched& S, const Epi& E) {
;     ...
;             PG8_WAIT_V(8); PG8_WAIT_L(0); PG8_BAR; PG8_MMA(1, 0, At, B0); PG8_MMA(1, 1, At, B1); PG8_BAR; PG8_SCHED;
;             PG8_LDB(B0, 1, 0); PG8_LDB(B1, 1, 1); PG8_SCHED; PG8_LDA(At, 1, 0); PG8_STAGE(PG8_SA(0, 1), a2 + hstep, voffA);
;             PG8_WAIT_V(8); PG8_WAIT_L(0); PG8_BAR; PG8_MMA(0, 0, At, B0); PG8_MMA(0, 1, At, B1); PG8_BAR; PG8_SCHED;
	s_setprio 1
	s_waitcnt lgkmcnt(0)
	v_mfma_f32_16x16x32_bf16 v[30:33], v[154:157], v[206:209], v[30:33]
	v_mfma_f32_16x16x32_bf16 v[26:29], v[166:169], v[206:209], v[26:29]
	v_mfma_f32_16x16x32_bf16 v[14:17], v[154:157], v[214:217], v[14:17]
	v_mfma_f32_16x16x32_bf16 v[10:13], v[166:169], v[214:217], v[10:13]
	v_mfma_f32_16x16x32_bf16 v[62:65], v[158:161], v[194:197], v[62:65]
	v_mfma_f32_16x16x32_bf16 v[58:61], v[170:173], v[194:197], v[58:61]
	v_mfma_f32_16x16x32_bf16 v[46:49], v[158:161], v[202:205], v[46:49]
	v_mfma_f32_16x16x32_bf16 v[42:45], v[170:173], v[202:205], v[42:45]
	v_mfma_f32_16x16x32_bf16 v[30:33], v[158:161], v[210:213], v[30:33]
	v_mfma_f32_16x16x32_bf16 v[26:29], v[170:173], v[210:213], v[26:29]
	v_mfma_f32_16x16x32_bf16 v[14:17], v[158:161], v[218:221], v[14:17]
	v_mfma_f32_16x16x32_bf16 v[10:13], v[170:173], v[218:221], v[10:13]
	s_setprio 0
	s_setprio 1
	v_mfma_f32_16x16x32_bf16 v[54:57], v[174:177], v[190:193], v[54:57]
	v_mfma_f32_16x16x32_bf16 v[50:53], v[182:185], v[190:193], v[50:53]
	v_mfma_f32_16x16x32_bf16 v[38:41], v[174:177], v[198:201], v[38:41]
	v_mfma_f32_16x16x32_bf16 v[34:37], v[182:185], v[198:201], v[34:37]
	v_mfma_f32_16x16x32_bf16 v[22:25], v[174:177], v[206:209], v[22:25]
	v_mfma_f32_16x16x32_bf16 v[18:21], v[182:185], v[206:209], v[18:21]
	v_mfma_f32_16x16x32_bf16 v[6:9], v[174:177], v[214:217], v[6:9]
	v_mfma_f32_16x16x32_bf16 v[2:5], v[182:185], v[214:217], v[2:5]
	v_mfma_f32_16x16x32_bf16 v[54:57], v[178:181], v[194:197], v[54:57]
	v_mfma_f32_16x16x32_bf16 v[50:53], v[186:189], v[194:197], v[50:53]
	v_mfma_f32_16x16x32_bf16 v[38:41], v[178:181], v[202:205], v[38:41]
	v_mfma_f32_16x16x32_bf16 v[34:37], v[186:189], v[202:205], v[34:37]
	v_mfma_f32_16x16x32_bf16 v[22:25], v[178:181], v[210:213], v[22:25]
	v_mfma_f32_16x16x32_bf16 v[18:21], v[186:189], v[210:213], v[18:21]
	v_mfma_f32_16x16x32_bf16 v[6:9], v[178:181], v[218:221], v[6:9]
	v_mfma_f32_16x16x32_bf16 v[2:5], v[186:189], v[218:221], v[2:5]
	s_setprio 0
	s_barrier
	s_add_i32 s51, 0, 0x18000
	v_add_u32_e32 v165, s51, v152
	s_add_i32 s52, 0, 0x1c000
	ds_read_b128 v[154:157], v165
	ds_read_b128 v[158:161], v165 offset:1024
	ds_read_b128 v[166:169], v165 offset:2048
	ds_read_b128 v[170:173], v165 offset:3072
	v_add_u32_e32 v165, s52, v152
	ds_read_b128 v[174:177], v165
	ds_read_b128 v[178:181], v165 offset:1024
	ds_read_b128 v[182:185], v165 offset:2048
	ds_read_b128 v[186:189], v165 offset:3072
	s_add_u32 s14, s14, 0x40000
	s_addc_u32 s15, s15, 0
	s_mov_b32 m0, s33
	v_lshl_add_u64 v[228:229], s[14:15], 0, v[130:131]
	ds_read_b128 v[190:193], v153 offset:32768
	ds_read_b128 v[194:197], v153 offset:33792
	ds_read_b128 v[198:201], v153 offset:34816
	ds_read_b128 v[202:205], v153 offset:35840
	ds_read_b128 v[206:209], v153 offset:36864
	ds_read_b128 v[210:213], v153 offset:37888
	ds_read_b128 v[214:217], v153 offset:38912
	ds_read_b128 v[218:221], v153 offset:39936
	global_load_lds_dwordx4 v[228:229], off
	v_lshl_add_u64 v[228:229], s[14:15], 0, v[134:135]
	s_mov_b32 m0, s34
	s_nop 0
	global_load_lds_dwordx4 v[228:229], off
	s_waitcnt vmcnt(8)
	s_waitcnt lgkmcnt(0)
	v_mfma_f32_16x16x32_bf16 v[94:97], v[154:157], v[190:193], v[94:97]
	v_mfma_f32_16x16x32_bf16 v[102:105], v[166:169], v[190:193], v[102:105]
	v_mfma_f32_16x16x32_bf16 v[106:109], v[154:157], v[198:201], v[106:109]
	v_mfma_f32_16x16x32_bf16 v[110:113], v[166:169], v[198:201], v[110:113]
	s_barrier
	s_setprio 1
	s_waitcnt lgkmcnt(0)
	v_mfma_f32_16x16x32_bf16 v[114:117], v[154:157], v[206:209], v[114:117]
	v_mfma_f32_16x16x32_bf16 v[122:125], v[166:169], v[206:209], v[122:125]
	v_mfma_f32_16x16x32_bf16 v[126:129], v[154:157], v[214:217], v[126:129]
	v_mfma_f32_16x16x32_bf16 v[118:121], v[166:169], v[214:217], v[118:121]
	v_mfma_f32_16x16x32_bf16 v[94:97], v[158:161], v[194:197], v[94:97]
	v_mfma_f32_16x16x32_bf16 v[102:105], v[170:173], v[194:197], v[102:105]
	v_mfma_f32_16x16x32_bf16 v[106:109], v[158:161], v[202:205], v[106:109]
	v_mfma_f32_16x16x32_bf16 v[110:113], v[170:173], v[202:205], v[110:113]
	v_mfma_f32_16x16x32_bf16 v[114:117], v[158:161], v[210:213], v[114:117]
	v_mfma_f32_16x16x32_bf16 v[122:125], v[170:173], v[210:213], v[122:125]
	v_mfma_f32_16x16x32_bf16 v[126:129], v[158:161], v[218:221], v[126:129]
	v_mfma_f32_16x16x32_bf16 v[118:121], v[170:173], v[218:221], v[118:121]
	s_setprio 0
	s_setprio 1
	v_mfma_f32_16x16x32_bf16 v[90:93], v[174:177], v[190:193], v[90:93]
	v_mfma_f32_16x16x32_bf16 v[74:77], v[182:185], v[190:193], v[74:77]
	v_mfma_f32_16x16x32_bf16 v[78:81], v[174:177], v[198:201], v[78:81]
	v_mfma_f32_16x16x32_bf16 v[66:69], v[182:185], v[198:201], v[66:69]
	v_mfma_f32_16x16x32_bf16 v[98:101], v[174:177], v[206:209], v[98:101]
	v_mfma_f32_16x16x32_bf16 v[86:89], v[182:185], v[206:209], v[86:89]
	v_mfma_f32_16x16x32_bf16 v[82:85], v[174:177], v[214:217], v[82:85]
	v_mfma_f32_16x16x32_bf16 v[70:73], v[182:185], v[214:217], v[70:73]
	v_mfma_f32_16x16x32_bf16 v[90:93], v[178:181], v[194:197], v[90:93]
	v_mfma_f32_16x16x32_bf16 v[74:77], v[186:189], v[194:197], v[74:77]
	v_mfma_f32_16x16x32_bf16 v[78:81], v[178:181], v[202:205], v[78:81]
	v_mfma_f32_16x16x32_bf16 v[66:69], v[186:189], v[202:205], v[66:69]
	v_mfma_f32_16x16x32_bf16 v[98:101], v[178:181], v[210:213], v[98:101]
	v_mfma_f32_16x16x32_bf16 v[86:89], v[186:189], v[210:213], v[86:89]
	v_mfma_f32_16x16x32_bf16 v[82:85], v[178:181], v[218:221], v[82:85]
	v_mfma_f32_16x16x32_bf16 v[70:73], v[186:189], v[218:221], v[70:73]
	s_setprio 0
	s_barrier
; #define PG8_STAGE(bufoff, gbase, voff) do { _Pragma("unroll") for (int _i = 0; _i < 2; ++_i) \
;         __builtin_amdgcn_global_load_lds((const unsigned*)((const char*)(gbase) + (voff)[_i]), (PG8_LAS unsigned*)(lds + (bufoff) + ldsw + _i * 8192), 16, 0, 0); } while (0)
; #define PG8_LDA(dst, b, h) do { _Pragma("unroll") for (int m = 0; m < 4; ++m) _Pragma("unroll") for (int k = 0; k < 2; ++k) dst[m][k] = *(const PG8_LAS bf16x8*)(lds + PG8_SA(b, h) + aoff + m * 2048 + k * 1024); } while (0)
; #define PG8_MMA(ai, bj, At, Bt) do { __builtin_amdgcn_s_setprio(1); _Pragma("unroll") for (int m = 0; m < 4; ++m) _Pragma("unroll") for (int n = 0; n < 2; ++n) _Pragma("unroll") for (int k = 0; k < 2; ++k) \
;         acc[ai][bj][m][n] = __builtin_amdgcn_mfma_f32_16x16x32_bf16(Bt[n][k], At[m][k], acc[ai][bj][m][n], 0, 0, 0); __builtin_amdgcn_s_setprio(0); } while (0)
; #define PG8_WAIT_V(n) asm volatile("s_waitcnt vmcnt(" #n ")" ::: "memory")
; #define PG8_WAIT_L(n) asm volatile("s_waitcnt lgkmcnt(" #n ")" ::: "memory")
; #define PG8_BAR __builtin_amdgcn_s_barrier()
; #define PG8_SCHED __builtin_amdgcn_sched_barrier(0)
; template <class Epi, class Sched, bool ALIGN_EPI = false, bool SP2 = false>
; __device__ __forceinline__ void gemm_phase(PG8_LAS unsigned char* lds, const Gemm g, const Sched& S, const Epi& E) {
;     ...
;             PG8_LDA(At, 1, 1); PG8_STAGE(PG8_SB(1, 0), b3, voffB); PG8_STAGE(PG8_SB(1, 1), b3 + hstep, voffB); PG8_STAGE(PG8_SA(1, 0), a3, voffA);
;             PG8_WAIT_V(8); PG8_WAIT_L(0); PG8_BAR; PG8_MMA(1, 0, At, B0); PG8_MMA(1, 1, At, B1); PG8_BAR; PG8_SCHED;
;     ...
;         if (!has_next) break;
; #pragma unroll
;         for (int a = 0; a < 2; ++a)
; #pragma unroll
;             for (int b = 0; b < 2; ++b)
; #pragma unroll
;                 for (int m = 0; m < 4; ++m)
; #pragma unroll
;                     for (int n = 0; n < 2; ++n) acc[a][b][m][n] = (f32x4){0.f, 0.f, 0.f, 0.f};
	s_add_i32 s14, s51, s21
	v_lshl_add_u64 v[162:163], v[162:163], 0, s[22:23]
	s_mov_b32 m0, s14
	ds_read_b128 v[190:193], v153 offset:49152
	ds_read_b128 v[194:197], v153 offset:50176
	ds_read_b128 v[198:201], v153 offset:51200
	ds_read_b128 v[202:205], v153 offset:52224
	ds_read_b128 v[206:209], v153 offset:53248
	ds_read_b128 v[210:213], v153 offset:54272
	ds_read_b128 v[214:217], v153 offset:55296
	ds_read_b128 v[218:221], v153 offset:56320
	global_load_lds_dwordx4 v[162:163], off
	s_add_i32 m0, s14, 0x2000
	s_add_u32 s2, s2, 0x40080
	v_lshl_add_u64 v[162:163], v[222:223], 0, s[22:23]
	s_addc_u32 s3, s3, 0
	s_add_i32 s14, s52, s21
	global_load_lds_dwordx4 v[162:163], off
	v_lshl_add_u64 v[162:163], s[2:3], 0, v[132:133]
	s_mov_b32 m0, s14
	s_nop 0
	global_load_lds_dwordx4 v[162:163], off
	v_lshl_add_u64 v[162:163], s[2:3], 0, v[136:137]
	s_add_i32 m0, s14, 0x2000
	s_nop 0
	global_load_lds_dwordx4 v[162:163], off
	v_lshl_add_u64 v[162:163], v[224:225], 0, s[22:23]
	s_mov_b32 m0, s37
	s_nop 0
	global_load_lds_dwordx4 v[162:163], off
	v_lshl_add_u64 v[162:163], v[226:227], 0, s[22:23]
	s_mov_b32 m0, s42
	s_nop 0
	global_load_lds_dwordx4 v[162:163], off
	s_waitcnt vmcnt(8)
	s_waitcnt lgkmcnt(0)
	v_mfma_f32_16x16x32_bf16 v[62:65], v[154:157], v[190:193], v[62:65]
	v_mfma_f32_16x16x32_bf16 v[58:61], v[166:169], v[190:193], v[58:61]
	v_mfma_f32_16x16x32_bf16 v[46:49], v[154:157], v[198:201], v[46:49]
	v_mfma_f32_16x16x32_bf16 v[42:45], v[166:169], v[198:201], v[42:45]
	s_barrier
	s_setprio 1
	s_waitcnt lgkmcnt(0)
	v_mfma_f32_16x16x32_bf16 v[30:33], v[154:157], v[206:209], v[30:33]
	v_mfma_f32_16x16x32_bf16 v[26:29], v[166:169], v[206:209], v[26:29]
	v_mfma_f32_16x16x32_bf16 v[14:17], v[154:157], v[214:217], v[14:17]
	v_mfma_f32_16x16x32_bf16 v[10:13], v[166:169], v[214:217], v[10:13]
	v_mfma_f32_16x16x32_bf16 v[62:65], v[158:161], v[194:197], v[62:65]
	v_mfma_f32_16x16x32_bf16 v[58:61], v[170:173], v[194:197], v[58:61]
	v_mfma_f32_16x16x32_bf16 v[46:49], v[158:161], v[202:205], v[46:49]
	v_mfma_f32_16x16x32_bf16 v[42:45], v[170:173], v[202:205], v[42:45]
	v_mfma_f32_16x16x32_bf16 v[30:33], v[158:161], v[210:213], v[30:33]
	v_mfma_f32_16x16x32_bf16 v[26:29], v[170:173], v[210:213], v[26:29]
	v_mfma_f32_16x16x32_bf16 v[14:17], v[158:161], v[218:221], v[14:17]
	v_mfma_f32_16x16x32_bf16 v[10:13], v[170:173], v[218:221], v[10:13]
	s_setprio 0
	s_setprio 1
	v_mfma_f32_16x16x32_bf16 v[54:57], v[174:177], v[190:193], v[54:57]
	v_mfma_f32_16x16x32_bf16 v[50:53], v[182:185], v[190:193], v[50:53]
	v_mfma_f32_16x16x32_bf16 v[38:41], v[174:177], v[198:201], v[38:41]
	v_mfma_f32_16x16x32_bf16 v[34:37], v[182:185], v[198:201], v[34:37]
	v_mfma_f32_16x16x32_bf16 v[22:25], v[174:177], v[206:209], v[22:25]
	v_mfma_f32_16x16x32_bf16 v[18:21], v[182:185], v[206:209], v[18:21]
	v_mfma_f32_16x16x32_bf16 v[6:9], v[174:177], v[214:217], v[6:9]
	v_mfma_f32_16x16x32_bf16 v[2:5], v[182:185], v[214:217], v[2:5]
	v_mfma_f32_16x16x32_bf16 v[54:57], v[178:181], v[194:197], v[54:57]
	v_mfma_f32_16x16x32_bf16 v[50:53], v[186:189], v[194:197], v[50:53]
	v_mfma_f32_16x16x32_bf16 v[38:41], v[178:181], v[202:205], v[38:41]
	v_mfma_f32_16x16x32_bf16 v[34:37], v[186:189], v[202:205], v[34:37]
	v_mfma_f32_16x16x32_bf16 v[22:25], v[178:181], v[210:213], v[22:25]
	v_mfma_f32_16x16x32_bf16 v[18:21], v[186:189], v[210:213], v[18:21]
	v_mfma_f32_16x16x32_bf16 v[6:9], v[178:181], v[218:221], v[6:9]
	v_mfma_f32_16x16x32_bf16 v[2:5], v[186:189], v[218:221], v[2:5]
	s_setprio 0
	s_barrier
	s_add_i32 s50, s50, 2
	s_add_u32 s40, s40, 0x100
	s_addc_u32 s41, s41, 0
	s_cmp_gt_u32 s50, 13
	s_cbranch_scc0 .LBB0_1488
	s_add_u32 s2, s46, 0xffffff00
	s_addc_u32 s3, s47, -1
	s_andn2_b64 vcc, exec, s[8:9]
	s_cbranch_vccnz .LBB0_1491
	v_mov_b32_e32 v2, 0
	s_mov_b32 s20, s24
	s_mov_b32 s12, s28
	s_mov_b64 s[0:1], s[38:39]
	s_mov_b32 s36, s45
	v_mov_b32_e32 v3, v2
	v_mov_b64_e32 v[4:5], v[2:3]
	v_mov_b64_e32 v[6:7], v[2:3]
	v_mov_b64_e32 v[8:9], v[2:3]
	v_mov_b64_e32 v[18:19], v[2:3]
	v_mov_b64_e32 v[20:21], v[2:3]
	v_mov_b64_e32 v[22:23], v[2:3]
	v_mov_b64_e32 v[24:25], v[2:3]
	v_mov_b64_e32 v[34:35], v[2:3]
	v_mov_b64_e32 v[36:37], v[2:3]
	v_mov_b64_e32 v[38:39], v[2:3]
	v_mov_b64_e32 v[40:41], v[2:3]
	v_mov_b64_e32 v[50:51], v[2:3]
	v_mov_b64_e32 v[52:53], v[2:3]
	v_mov_b64_e32 v[54:55], v[2:3]
	v_mov_b64_e32 v[56:57], v[2:3]
	v_mov_b64_e32 v[10:11], v[2:3]
	v_mov_b64_e32 v[12:13], v[2:3]
	v_mov_b64_e32 v[14:15], v[2:3]
	v_mov_b64_e32 v[16:17], v[2:3]
	v_mov_b64_e32 v[26:27], v[2:3]
	v_mov_b64_e32 v[28:29], v[2:3]
	v_mov_b64_e32 v[30:31], v[2:3]
	v_mov_b64_e32 v[32:33], v[2:3]
	v_mov_b64_e32 v[42:43], v[2:3]
	v_mov_b64_e32 v[44:45], v[2:3]
	v_mov_b64_e32 v[46:47], v[2:3]
	v_mov_b64_e32 v[48:49], v[2:3]
	v_mov_b64_e32 v[58:59], v[2:3]
	v_mov_b64_e32 v[60:61], v[2:3]
	v_mov_b64_e32 v[62:63], v[2:3]
	v_mov_b64_e32 v[64:65], v[2:3]
	v_mov_b64_e32 v[70:71], v[2:3]
	v_mov_b64_e32 v[72:73], v[2:3]
	v_mov_b64_e32 v[82:83], v[2:3]
	v_mov_b64_e32 v[84:85], v[2:3]
	v_mov_b64_e32 v[86:87], v[2:3]
	v_mov_b64_e32 v[88:89], v[2:3]
	v_mov_b64_e32 v[98:99], v[2:3]
	v_mov_b64_e32 v[100:101], v[2:3]
	v_mov_b64_e32 v[66:67], v[2:3]
	v_mov_b64_e32 v[68:69], v[2:3]
	v_mov_b64_e32 v[78:79], v[2:3]
	v_mov_b64_e32 v[80:81], v[2:3]
	v_mov_b64_e32 v[74:75], v[2:3]
	v_mov_b64_e32 v[76:77], v[2:3]
	v_mov_b64_e32 v[90:91], v[2:3]
	v_mov_b64_e32 v[92:93], v[2:3]
	v_mov_b64_e32 v[118:119], v[2:3]
	v_mov_b64_e32 v[120:121], v[2:3]
	v_mov_b64_e32 v[126:127], v[2:3]
	v_mov_b64_e32 v[128:129], v[2:3]
	v_mov_b64_e32 v[122:123], v[2:3]
	v_mov_b64_e32 v[124:125], v[2:3]
	v_mov_b64_e32 v[114:115], v[2:3]
	v_mov_b64_e32 v[116:117], v[2:3]
	v_mov_b64_e32 v[110:111], v[2:3]
	v_mov_b64_e32 v[112:113], v[2:3]
	v_mov_b64_e32 v[106:107], v[2:3]
	v_mov_b64_e32 v[108:109], v[2:3]
	v_mov_b64_e32 v[102:103], v[2:3]
	v_mov_b64_e32 v[104:105], v[2:3]
	v_mov_b64_e32 v[94:95], v[2:3]
	v_mov_b64_e32 v[96:97], v[2:3]
	s_branch .LBB0_1492

; #define PG8_STAGE(bufoff, gbase, voff) do { _Pragma("unroll") for (int _i = 0; _i < 2; ++_i) \
;         __builtin_amdgcn_global_load_lds((const unsigned*)((const char*)(gbase) + (voff)[_i]), (PG8_LAS unsigned*)(lds + (bufoff) + ldsw + _i * 8192), 16, 0, 0); } while (0)
; #define PG8_LDA(dst, b, h) do { _Pragma("unroll") for (int m = 0; m < 4; ++m) _Pragma("unroll") for (int k = 0; k < 2; ++k) dst[m][k] = *(const PG8_LAS bf16x8*)(lds + PG8_SA(b, h) + aoff + m * 2048 + k * 1024); } while (0)
; #define PG8_LDB(dst, b, h) do { _Pragma("unroll") for (int n = 0; n < 2; ++n) _Pragma("unroll") for (int k = 0; k < 2; ++k) dst[n][k] = *(const PG8_LAS bf16x8*)(lds + PG8_SB(b, h) + boff + n * 2048 + k * 1024); } while (0)
; #define PG8_MMA(ai, bj, At, Bt) do { __builtin_amdgcn_s_setprio(1); _Pragma("unroll") for (int m = 0; m < 4; ++m) _Pragma("unroll") for (int n = 0; n < 2; ++n) _Pragma("unroll") for (int k = 0; k < 2; ++k) \
;         acc[ai][bj][m][n] = __builtin_amdgcn_mfma_f32_16x16x32_bf16(Bt[n][k], At[m][k], acc[ai][bj][m][n], 0, 0, 0); __builtin_amdgcn_s_setprio(0); } while (0)
; #define PG8_WAIT_V(n) asm volatile("s_waitcnt vmcnt(" #n ")" ::: "memory")
; #define PG8_BAR __builtin_amdgcn_s_barrier()
; template <class Epi, class Sched, bool ALIGN_EPI = false, bool SP2 = false>
; __device__ __forceinline__ void gemm_phase(PG8_LAS unsigned char* lds, const Gemm g, const Sched& S, const Epi& E) {
;     ...
;         for (int t = 0; t < nt; t += 2) {
;             const bool last = (t == nt - 2);
;             const char* a1 = cA + (size_t)(t + 1) * kstep;
;             const char* a2 = last ? nA : cA + (size_t)(t + 2) * kstep; const char* b2 = last ? nB : cB + (size_t)(t + 2) * kstep;
;             const char* a3 = a2 + kstep; const char* b3 = b2 + kstep;
;             if (last && has_next) S.a_ready(nxt);
;             if constexpr (SP2) {
;             PG8_LDB(B0, 0, 0); PG8_LDB(B1, 0, 1); PG8_SCHED; PG8_LDA(At, 0, 0); PG8_STAGE(PG8_SA(1, 1), a1 + hstep, voffA);
;             PG8_WAIT_V(8); PG8_WAIT_L(0); PG8_BAR; PG8_MMA(0, 0, At, B0); PG8_MMA(0, 1, At, B1); PG8_BAR; PG8_SCHED;
;             PG8_LDA(At, 0, 1); PG8_STAGE(PG8_SB(0, 0), b2, voffB); PG8_STAGE(PG8_SB(0, 1), b2 + hstep, voffB); PG8_STAGE(PG8_SA(0, 0), a2, voffA);
;             PG8_WAIT_V(8); PG8_WAIT_L(0); PG8_BAR; PG8_MMA(1, 0, At, B0); PG8_MMA(1, 1, At, B1); PG8_BAR; PG8_SCHED;
.LBB0_1628:
	ds_read_b128 v[146:149], v153
	ds_read_b128 v[156:159], v153 offset:1024
	ds_read_b128 v[160:163], v153 offset:2048
	ds_read_b128 v[164:167], v153 offset:3072
	ds_read_b128 v[168:171], v154
	ds_read_b128 v[172:175], v154 offset:1024
	ds_read_b128 v[176:179], v154 offset:2048
	ds_read_b128 v[180:183], v154 offset:3072
	s_add_u32 s2, s36, 0xfffc0080
	s_addc_u32 s3, s37, -1
	s_cmp_eq_u32 s48, 12
	s_cselect_b32 s15, s23, s3
	s_cselect_b32 s14, s46, s2
	s_cselect_b32 s3, s21, s35
	s_cselect_b32 s2, s47, s34
	v_lshl_add_u64 v[216:217], s[36:37], 0, v[138:139]
	s_add_i32 m0, s26, 0xc000
	ds_read_b128 v[184:187], v155
	ds_read_b128 v[188:191], v155 offset:1024
	ds_read_b128 v[192:195], v155 offset:2048
	ds_read_b128 v[196:199], v155 offset:3072
	ds_read_b128 v[200:203], v155 offset:4096
	ds_read_b128 v[204:207], v155 offset:5120
	ds_read_b128 v[208:211], v155 offset:6144
	ds_read_b128 v[212:215], v155 offset:7168
	global_load_lds_dwordx4 v[216:217], off
	v_lshl_add_u64 v[216:217], s[36:37], 0, v[140:141]
	s_add_i32 m0, s26, 0xe000
	s_nop 0
	global_load_lds_dwordx4 v[216:217], off
	s_waitcnt vmcnt(8)
	s_waitcnt lgkmcnt(0)
	v_mfma_f32_16x16x32_bf16 v[126:129], v[146:149], v[184:187], v[126:129]
	v_mfma_f32_16x16x32_bf16 v[122:125], v[160:163], v[184:187], v[122:125]
	v_mfma_f32_16x16x32_bf16 v[110:113], v[146:149], v[192:195], v[110:113]
	v_mfma_f32_16x16x32_bf16 v[106:109], v[160:163], v[192:195], v[106:109]
	s_barrier
	s_setprio 1
	s_waitcnt lgkmcnt(0)
	v_mfma_f32_16x16x32_bf16 v[94:97], v[146:149], v[200:203], v[94:97]
	v_mfma_f32_16x16x32_bf16 v[90:93], v[160:163], v[200:203], v[90:93]
	v_mfma_f32_16x16x32_bf16 v[78:81], v[146:149], v[208:211], v[78:81]
	v_mfma_f32_16x16x32_bf16 v[74:77], v[160:163], v[208:211], v[74:77]
	v_mfma_f32_16x16x32_bf16 v[126:129], v[156:159], v[188:191], v[126:129]
	v_mfma_f32_16x16x32_bf16 v[122:125], v[164:167], v[188:191], v[122:125]
	v_mfma_f32_16x16x32_bf16 v[110:113], v[156:159], v[196:199], v[110:113]
	v_mfma_f32_16x16x32_bf16 v[106:109], v[164:167], v[196:199], v[106:109]
	v_mfma_f32_16x16x32_bf16 v[94:97], v[156:159], v[204:207], v[94:97]
	v_mfma_f32_16x16x32_bf16 v[90:93], v[164:167], v[204:207], v[90:93]
	v_mfma_f32_16x16x32_bf16 v[78:81], v[156:159], v[212:215], v[78:81]
	v_mfma_f32_16x16x32_bf16 v[74:77], v[164:167], v[212:215], v[74:77]
	s_setprio 0
	s_setprio 1
	v_mfma_f32_16x16x32_bf16 v[118:121], v[168:171], v[184:187], v[118:121]
	v_mfma_f32_16x16x32_bf16 v[114:117], v[176:179], v[184:187], v[114:117]
	v_mfma_f32_16x16x32_bf16 v[102:105], v[168:171], v[192:195], v[102:105]
	v_mfma_f32_16x16x32_bf16 v[98:101], v[176:179], v[192:195], v[98:101]
	v_mfma_f32_16x16x32_bf16 v[86:89], v[168:171], v[200:203], v[86:89]
	v_mfma_f32_16x16x32_bf16 v[82:85], v[176:179], v[200:203], v[82:85]
	v_mfma_f32_16x16x32_bf16 v[70:73], v[168:171], v[208:211], v[70:73]
	v_mfma_f32_16x16x32_bf16 v[66:69], v[176:179], v[208:211], v[66:69]
	v_mfma_f32_16x16x32_bf16 v[118:121], v[172:175], v[188:191], v[118:121]
	v_mfma_f32_16x16x32_bf16 v[114:117], v[180:183], v[188:191], v[114:117]
	v_mfma_f32_16x16x32_bf16 v[102:105], v[172:175], v[196:199], v[102:105]
	v_mfma_f32_16x16x32_bf16 v[98:101], v[180:183], v[196:199], v[98:101]
	v_mfma_f32_16x16x32_bf16 v[86:89], v[172:175], v[204:207], v[86:89]
	v_mfma_f32_16x16x32_bf16 v[82:85], v[180:183], v[204:207], v[82:85]
	v_mfma_f32_16x16x32_bf16 v[70:73], v[172:175], v[212:215], v[70:73]
	v_mfma_f32_16x16x32_bf16 v[66:69], v[180:183], v[212:215], v[66:69]
	s_setprio 0
	s_barrier
	s_add_i32 s49, s42, s17
	v_lshl_add_u64 v[216:217], s[2:3], 0, v[132:133]
	s_mov_b32 m0, s49
	ds_read_b128 v[184:187], v155 offset:16384
	ds_read_b128 v[188:191], v155 offset:17408
	ds_read_b128 v[192:195], v155 offset:18432
	ds_read_b128 v[196:199], v155 offset:19456
	ds_read_b128 v[200:203], v155 offset:20480
	ds_read_b128 v[204:207], v155 offset:21504
	ds_read_b128 v[208:211], v155 offset:22528
	ds_read_b128 v[212:215], v155 offset:23552
	global_load_lds_dwordx4 v[216:217], off
	s_add_i32 m0, s49, 0x2000
	s_add_u32 s50, s2, 0x40000
	v_lshl_add_u64 v[218:219], s[2:3], 0, v[136:137]
	s_addc_u32 s51, s3, 0
	s_add_i32 s49, s43, s17
	global_load_lds_dwordx4 v[218:219], off
	v_lshl_add_u64 v[220:221], s[50:51], 0, v[132:133]
	s_mov_b32 m0, s49
	v_lshl_add_u64 v[222:223], s[14:15], 0, v[134:135]
	global_load_lds_dwordx4 v[220:221], off
	v_lshl_add_u64 v[220:221], s[50:51], 0, v[136:137]
	s_add_i32 m0, s49, 0x2000
	s_nop 0
	global_load_lds_dwordx4 v[220:221], off
	v_lshl_add_u64 v[220:221], s[14:15], 0, v[130:131]
	s_mov_b32 m0, s26
	s_nop 0
	global_load_lds_dwordx4 v[220:221], off
	s_mov_b32 m0, s27
	s_nop 0
	global_load_lds_dwordx4 v[222:223], off
	s_waitcnt vmcnt(8)
	s_waitcnt lgkmcnt(0)
	v_mfma_f32_16x16x32_bf16 v[62:65], v[146:149], v[184:187], v[62:65]
	v_mfma_f32_16x16x32_bf16 v[58:61], v[160:163], v[184:187], v[58:61]
	v_mfma_f32_16x16x32_bf16 v[46:49], v[146:149], v[192:195], v[46:49]
	v_mfma_f32_16x16x32_bf16 v[42:45], v[160:163], v[192:195], v[42:45]
	s_barrier
; #define PG8_STAGE(bufoff, gbase, voff) do { _Pragma("unroll") for (int _i = 0; _i < 2; ++_i) \
;         __builtin_amdgcn_global_load_lds((const unsigned*)((const char*)(gbase) + (voff)[_i]), (PG8_LAS unsigned*)(lds + (bufoff) + ldsw + _i * 8192), 16, 0, 0); } while (0)
; #define PG8_LDA(dst, b, h) do { _Pragma("unroll") for (int m = 0; m < 4; ++m) _Pragma("unroll") for (int k = 0; k < 2; ++k) dst[m][k] = *(const PG8_LAS bf16x8*)(lds + PG8_SA(b, h) + aoff + m * 2048 + k * 1024); } while (0)
; #define PG8_LDB(dst, b, h) do { _Pragma("unroll") for (int n = 0; n < 2; ++n) _Pragma("unroll") for (int k = 0; k < 2; ++k) dst[n][k] = *(const PG8_LAS bf16x8*)(lds + PG8_SB(b, h) + boff + n * 2048 + k * 1024); } while (0)
; #define PG8_MMA(ai, bj, At, Bt) do { __builtin_amdgcn_s_setprio(1); _Pragma("unroll") for (int m = 0; m < 4; ++m) _Pragma("unroll") for (int n = 0; n < 2; ++n) _Pragma("unroll") for (int k = 0; k < 2; ++k) \
;         acc[ai][bj][m][n] = __builtin_amdgcn_mfma_f32_16x16x32_bf16(Bt[n][k], At[m][k], acc[ai][bj][m][n], 0, 0, 0); __builtin_amdgcn_s_setprio(0); } while (0)
; #define PG8_WAIT_V(n) asm volatile("s_waitcnt vmcnt(" #n ")" ::: "memory")
; #define PG8_WAIT_L(n) asm volatile("s_waitcnt lgkmcnt(" #n ")" ::: "memory")
; #define PG8_BAR __builtin_amdgcn_s_barrier()
; #define PG8_SCHED __builtin_amdgcn_sched_barrier(0)
; template <class Epi, class Sched, bool ALIGN_EPI = false, bool SP2 = false>
; __device__ __forceinline__ void gemm_phase(PG8_LAS unsigned char* lds, const Gemm g, const Sched& S, const Epi& E) {
;     ...
;             PG8_WAIT_V(8); PG8_WAIT_L(0); PG8_BAR; PG8_MMA(1, 0, At, B0); PG8_MMA(1, 1, At, B1); PG8_BAR; PG8_SCHED;
;             PG8_LDB(B0, 1, 0); PG8_LDB(B1, 1, 1); PG8_SCHED; PG8_LDA(At, 1, 0); PG8_STAGE(PG8_SA(0, 1), a2 + hstep, voffA);
;             PG8_WAIT_V(8); PG8_WAIT_L(0); PG8_BAR; PG8_MMA(0, 0, At, B0); PG8_MMA(0, 1, At, B1); PG8_BAR; PG8_SCHED;
	s_setprio 1
	s_waitcnt lgkmcnt(0)
	v_mfma_f32_16x16x32_bf16 v[30:33], v[146:149], v[200:203], v[30:33]
	v_mfma_f32_16x16x32_bf16 v[26:29], v[160:163], v[200:203], v[26:29]
	v_mfma_f32_16x16x32_bf16 v[14:17], v[146:149], v[208:211], v[14:17]
	v_mfma_f32_16x16x32_bf16 v[10:13], v[160:163], v[208:211], v[10:13]
	v_mfma_f32_16x16x32_bf16 v[62:65], v[156:159], v[188:191], v[62:65]
	v_mfma_f32_16x16x32_bf16 v[58:61], v[164:167], v[188:191], v[58:61]
	v_mfma_f32_16x16x32_bf16 v[46:49], v[156:159], v[196:199], v[46:49]
	v_mfma_f32_16x16x32_bf16 v[42:45], v[164:167], v[196:199], v[42:45]
	v_mfma_f32_16x16x32_bf16 v[30:33], v[156:159], v[204:207], v[30:33]
	v_mfma_f32_16x16x32_bf16 v[26:29], v[164:167], v[204:207], v[26:29]
	v_mfma_f32_16x16x32_bf16 v[14:17], v[156:159], v[212:215], v[14:17]
	v_mfma_f32_16x16x32_bf16 v[10:13], v[164:167], v[212:215], v[10:13]
	s_setprio 0
	s_setprio 1
	v_mfma_f32_16x16x32_bf16 v[54:57], v[168:171], v[184:187], v[54:57]
	v_mfma_f32_16x16x32_bf16 v[50:53], v[176:179], v[184:187], v[50:53]
	v_mfma_f32_16x16x32_bf16 v[38:41], v[168:171], v[192:195], v[38:41]
	v_mfma_f32_16x16x32_bf16 v[34:37], v[176:179], v[192:195], v[34:37]
	v_mfma_f32_16x16x32_bf16 v[22:25], v[168:171], v[200:203], v[22:25]
	v_mfma_f32_16x16x32_bf16 v[18:21], v[176:179], v[200:203], v[18:21]
	v_mfma_f32_16x16x32_bf16 v[6:9], v[168:171], v[208:211], v[6:9]
	v_mfma_f32_16x16x32_bf16 v[2:5], v[176:179], v[208:211], v[2:5]
	v_mfma_f32_16x16x32_bf16 v[54:57], v[172:175], v[188:191], v[54:57]
	v_mfma_f32_16x16x32_bf16 v[50:53], v[180:183], v[188:191], v[50:53]
	v_mfma_f32_16x16x32_bf16 v[38:41], v[172:175], v[196:199], v[38:41]
	v_mfma_f32_16x16x32_bf16 v[34:37], v[180:183], v[196:199], v[34:37]
	v_mfma_f32_16x16x32_bf16 v[22:25], v[172:175], v[204:207], v[22:25]
	v_mfma_f32_16x16x32_bf16 v[18:21], v[180:183], v[204:207], v[18:21]
	v_mfma_f32_16x16x32_bf16 v[6:9], v[172:175], v[212:215], v[6:9]
	v_mfma_f32_16x16x32_bf16 v[2:5], v[180:183], v[212:215], v[2:5]
	s_setprio 0
	s_barrier
	s_add_i32 s49, 0, 0x18000
	s_add_i32 s50, 0, 0x1c000
	v_add_u32_e32 v164, s49, v151
	v_add_u32_e32 v180, s50, v151
	ds_read_b128 v[146:149], v164
	ds_read_b128 v[156:159], v164 offset:1024
	ds_read_b128 v[160:163], v164 offset:2048
	ds_read_b128 v[164:167], v164 offset:3072
	ds_read_b128 v[168:171], v180
	ds_read_b128 v[172:175], v180 offset:1024
	ds_read_b128 v[176:179], v180 offset:2048
	ds_read_b128 v[180:183], v180 offset:3072
	s_add_u32 s14, s14, 0x40000
	s_addc_u32 s15, s15, 0
	s_mov_b32 m0, s31
	v_lshl_add_u64 v[224:225], s[14:15], 0, v[130:131]
	ds_read_b128 v[184:187], v155 offset:32768
	ds_read_b128 v[188:191], v155 offset:33792
	ds_read_b128 v[192:195], v155 offset:34816
	ds_read_b128 v[196:199], v155 offset:35840
	ds_read_b128 v[200:203], v155 offset:36864
	ds_read_b128 v[204:207], v155 offset:37888
	ds_read_b128 v[208:211], v155 offset:38912
	ds_read_b128 v[212:215], v155 offset:39936
	global_load_lds_dwordx4 v[224:225], off
	v_lshl_add_u64 v[224:225], s[14:15], 0, v[134:135]
	s_mov_b32 m0, s33
	s_nop 0
	global_load_lds_dwordx4 v[224:225], off
	s_waitcnt vmcnt(8)
	s_waitcnt lgkmcnt(0)
	v_mfma_f32_16x16x32_bf16 v[126:129], v[146:149], v[184:187], v[126:129]
	v_mfma_f32_16x16x32_bf16 v[122:125], v[160:163], v[184:187], v[122:125]
	v_mfma_f32_16x16x32_bf16 v[110:113], v[146:149], v[192:195], v[110:113]
	v_mfma_f32_16x16x32_bf16 v[106:109], v[160:163], v[192:195], v[106:109]
	s_barrier
	s_setprio 1
	s_waitcnt lgkmcnt(0)
	v_mfma_f32_16x16x32_bf16 v[94:97], v[146:149], v[200:203], v[94:97]
	v_mfma_f32_16x16x32_bf16 v[90:93], v[160:163], v[200:203], v[90:93]
	v_mfma_f32_16x16x32_bf16 v[78:81], v[146:149], v[208:211], v[78:81]
	v_mfma_f32_16x16x32_bf16 v[74:77], v[160:163], v[208:211], v[74:77]
	v_mfma_f32_16x16x32_bf16 v[126:129], v[156:159], v[188:191], v[126:129]
	v_mfma_f32_16x16x32_bf16 v[122:125], v[164:167], v[188:191], v[122:125]
	v_mfma_f32_16x16x32_bf16 v[110:113], v[156:159], v[196:199], v[110:113]
	v_mfma_f32_16x16x32_bf16 v[106:109], v[164:167], v[196:199], v[106:109]
	v_mfma_f32_16x16x32_bf16 v[94:97], v[156:159], v[204:207], v[94:97]
	v_mfma_f32_16x16x32_bf16 v[90:93], v[164:167], v[204:207], v[90:93]
	v_mfma_f32_16x16x32_bf16 v[78:81], v[156:159], v[212:215], v[78:81]
	v_mfma_f32_16x16x32_bf16 v[74:77], v[164:167], v[212:215], v[74:77]
	s_setprio 0
	s_setprio 1
	v_mfma_f32_16x16x32_bf16 v[118:121], v[168:171], v[184:187], v[118:121]
	v_mfma_f32_16x16x32_bf16 v[114:117], v[176:179], v[184:187], v[114:117]
	v_mfma_f32_16x16x32_bf16 v[102:105], v[168:171], v[192:195], v[102:105]
	v_mfma_f32_16x16x32_bf16 v[98:101], v[176:179], v[192:195], v[98:101]
	v_mfma_f32_16x16x32_bf16 v[86:89], v[168:171], v[200:203], v[86:89]
	v_mfma_f32_16x16x32_bf16 v[82:85], v[176:179], v[200:203], v[82:85]
	v_mfma_f32_16x16x32_bf16 v[70:73], v[168:171], v[208:211], v[70:73]
	v_mfma_f32_16x16x32_bf16 v[66:69], v[176:179], v[208:211], v[66:69]
	v_mfma_f32_16x16x32_bf16 v[118:121], v[172:175], v[188:191], v[118:121]
	v_mfma_f32_16x16x32_bf16 v[114:117], v[180:183], v[188:191], v[114:117]
	v_mfma_f32_16x16x32_bf16 v[102:105], v[172:175], v[196:199], v[102:105]
	v_mfma_f32_16x16x32_bf16 v[98:101], v[180:183], v[196:199], v[98:101]
	v_mfma_f32_16x16x32_bf16 v[86:89], v[172:175], v[204:207], v[86:89]
	v_mfma_f32_16x16x32_bf16 v[82:85], v[180:183], v[204:207], v[82:85]
	v_mfma_f32_16x16x32_bf16 v[70:73], v[172:175], v[212:215], v[70:73]
	v_mfma_f32_16x16x32_bf16 v[66:69], v[180:183], v[212:215], v[66:69]
	s_setprio 0
	s_barrier
; #define PG8_STAGE(bufoff, gbase, voff) do { _Pragma("unroll") for (int _i = 0; _i < 2; ++_i) \
;         __builtin_amdgcn_global_load_lds((const unsigned*)((const char*)(gbase) + (voff)[_i]), (PG8_LAS unsigned*)(lds + (bufoff) + ldsw + _i * 8192), 16, 0, 0); } while (0)
; #define PG8_LDA(dst, b, h) do { _Pragma("unroll") for (int m = 0; m < 4; ++m) _Pragma("unroll") for (int k = 0; k < 2; ++k) dst[m][k] = *(const PG8_LAS bf16x8*)(lds + PG8_SA(b, h) + aoff + m * 2048 + k * 1024); } while (0)
; #define PG8_MMA(ai, bj, At, Bt) do { __builtin_amdgcn_s_setprio(1); _Pragma("unroll") for (int m = 0; m < 4; ++m) _Pragma("unroll") for (int n = 0; n < 2; ++n) _Pragma("unroll") for (int k = 0; k < 2; ++k) \
;         acc[ai][bj][m][n] = __builtin_amdgcn_mfma_f32_16x16x32_bf16(Bt[n][k], At[m][k], acc[ai][bj][m][n], 0, 0, 0); __builtin_amdgcn_s_setprio(0); } while (0)
; #define PG8_WAIT_V(n) asm volatile("s_waitcnt vmcnt(" #n ")" ::: "memory")
; #define PG8_WAIT_L(n) asm volatile("s_waitcnt lgkmcnt(" #n ")" ::: "memory")
; #define PG8_BAR __builtin_amdgcn_s_barrier()
; #define PG8_SCHED __builtin_amdgcn_sched_barrier(0)
; template <class Epi, class Sched, bool ALIGN_EPI = false, bool SP2 = false>
; __device__ __forceinline__ void gemm_phase(PG8_LAS unsigned char* lds, const Gemm g, const Sched& S, const Epi& E) {
;     ...
;             PG8_LDA(At, 1, 1); PG8_STAGE(PG8_SB(1, 0), b3, voffB); PG8_STAGE(PG8_SB(1, 1), b3 + hstep, voffB); PG8_STAGE(PG8_SA(1, 0), a3, voffA);
;             PG8_WAIT_V(8); PG8_WAIT_L(0); PG8_BAR; PG8_MMA(1, 0, At, B0); PG8_MMA(1, 1, At, B1); PG8_BAR; PG8_SCHED;
;     ...
;         if constexpr (ALIGN_EPI) { if (wr == 0) PG8_BAR; }
	s_add_i32 s14, s49, s17
	v_lshl_add_u64 v[216:217], v[216:217], 0, s[12:13]
	s_mov_b32 m0, s14
	ds_read_b128 v[184:187], v155 offset:49152
	ds_read_b128 v[188:191], v155 offset:50176
	ds_read_b128 v[192:195], v155 offset:51200
	ds_read_b128 v[196:199], v155 offset:52224
	ds_read_b128 v[200:203], v155 offset:53248
	ds_read_b128 v[204:207], v155 offset:54272
	ds_read_b128 v[208:211], v155 offset:55296
	ds_read_b128 v[212:215], v155 offset:56320
	global_load_lds_dwordx4 v[216:217], off
	s_add_i32 m0, s14, 0x2000
	s_add_u32 s2, s2, 0x40080
	v_lshl_add_u64 v[216:217], v[218:219], 0, s[12:13]
	s_addc_u32 s3, s3, 0
	s_add_i32 s14, s50, s17
	global_load_lds_dwordx4 v[216:217], off
	v_lshl_add_u64 v[216:217], s[2:3], 0, v[132:133]
	s_mov_b32 m0, s14
	s_nop 0
	global_load_lds_dwordx4 v[216:217], off
	v_lshl_add_u64 v[216:217], s[2:3], 0, v[136:137]
	s_add_i32 m0, s14, 0x2000
	s_nop 0
	global_load_lds_dwordx4 v[216:217], off
	v_lshl_add_u64 v[216:217], v[220:221], 0, s[12:13]
	s_mov_b32 m0, s39
	s_nop 0
	global_load_lds_dwordx4 v[216:217], off
	v_lshl_add_u64 v[216:217], v[222:223], 0, s[12:13]
	s_mov_b32 m0, s40
	s_nop 0
	global_load_lds_dwordx4 v[216:217], off
	s_waitcnt vmcnt(8)
	s_waitcnt lgkmcnt(0)
	v_mfma_f32_16x16x32_bf16 v[62:65], v[146:149], v[184:187], v[62:65]
	v_mfma_f32_16x16x32_bf16 v[58:61], v[160:163], v[184:187], v[58:61]
	v_mfma_f32_16x16x32_bf16 v[46:49], v[146:149], v[192:195], v[46:49]
	v_mfma_f32_16x16x32_bf16 v[42:45], v[160:163], v[192:195], v[42:45]
	s_barrier
	s_setprio 1
	s_waitcnt lgkmcnt(0)
	v_mfma_f32_16x16x32_bf16 v[30:33], v[146:149], v[200:203], v[30:33]
	v_mfma_f32_16x16x32_bf16 v[26:29], v[160:163], v[200:203], v[26:29]
	v_mfma_f32_16x16x32_bf16 v[14:17], v[146:149], v[208:211], v[14:17]
	v_mfma_f32_16x16x32_bf16 v[10:13], v[160:163], v[208:211], v[10:13]
	v_mfma_f32_16x16x32_bf16 v[62:65], v[156:159], v[188:191], v[62:65]
	v_mfma_f32_16x16x32_bf16 v[58:61], v[164:167], v[188:191], v[58:61]
	v_mfma_f32_16x16x32_bf16 v[46:49], v[156:159], v[196:199], v[46:49]
	v_mfma_f32_16x16x32_bf16 v[42:45], v[164:167], v[196:199], v[42:45]
	v_mfma_f32_16x16x32_bf16 v[30:33], v[156:159], v[204:207], v[30:33]
	v_mfma_f32_16x16x32_bf16 v[26:29], v[164:167], v[204:207], v[26:29]
	v_mfma_f32_16x16x32_bf16 v[14:17], v[156:159], v[212:215], v[14:17]
	v_mfma_f32_16x16x32_bf16 v[10:13], v[164:167], v[212:215], v[10:13]
	s_setprio 0
	s_setprio 1
	v_mfma_f32_16x16x32_bf16 v[54:57], v[168:171], v[184:187], v[54:57]
	v_mfma_f32_16x16x32_bf16 v[50:53], v[176:179], v[184:187], v[50:53]
	v_mfma_f32_16x16x32_bf16 v[38:41], v[168:171], v[192:195], v[38:41]
	v_mfma_f32_16x16x32_bf16 v[34:37], v[176:179], v[192:195], v[34:37]
	v_mfma_f32_16x16x32_bf16 v[22:25], v[168:171], v[200:203], v[22:25]
	v_mfma_f32_16x16x32_bf16 v[18:21], v[176:179], v[200:203], v[18:21]
	v_mfma_f32_16x16x32_bf16 v[6:9], v[168:171], v[208:211], v[6:9]
	v_mfma_f32_16x16x32_bf16 v[2:5], v[176:179], v[208:211], v[2:5]
	v_mfma_f32_16x16x32_bf16 v[54:57], v[172:175], v[188:191], v[54:57]
	v_mfma_f32_16x16x32_bf16 v[50:53], v[180:183], v[188:191], v[50:53]
	v_mfma_f32_16x16x32_bf16 v[38:41], v[172:175], v[196:199], v[38:41]
	v_mfma_f32_16x16x32_bf16 v[34:37], v[180:183], v[196:199], v[34:37]
	v_mfma_f32_16x16x32_bf16 v[22:25], v[172:175], v[204:207], v[22:25]
	v_mfma_f32_16x16x32_bf16 v[18:21], v[180:183], v[204:207], v[18:21]
	v_mfma_f32_16x16x32_bf16 v[6:9], v[172:175], v[212:215], v[6:9]
	v_mfma_f32_16x16x32_bf16 v[2:5], v[180:183], v[212:215], v[2:5]
	s_setprio 0
	s_barrier
	s_add_i32 s48, s48, 2
	s_add_u32 s36, s36, 0x100
	s_addc_u32 s37, s37, 0
	s_add_u32 s34, s34, 0x100
	s_addc_u32 s35, s35, 0
	s_cmp_gt_u32 s48, 13
	s_cbranch_scc0 .LBB0_1628
	s_and_b64 vcc, exec, s[18:19]
	s_cbranch_vccz .LBB0_1631
	s_barrier

; #define PG8_STAGE(bufoff, gbase, voff) do { _Pragma("unroll") for (int _i = 0; _i < 2; ++_i) \
;         __builtin_amdgcn_global_load_lds((const unsigned*)((const char*)(gbase) + (voff)[_i]), (PG8_LAS unsigned*)(lds + (bufoff) + ldsw + _i * 8192), 16, 0, 0); } while (0)
; #define PG8_LDA(dst, b, h) do { _Pragma("unroll") for (int m = 0; m < 4; ++m) _Pragma("unroll") for (int k = 0; k < 2; ++k) dst[m][k] = *(const PG8_LAS bf16x8*)(lds + PG8_SA(b, h) + aoff + m * 2048 + k * 1024); } while (0)
; #define PG8_LDB(dst, b, h) do { _Pragma("unroll") for (int n = 0; n < 2; ++n) _Pragma("unroll") for (int k = 0; k < 2; ++k) dst[n][k] = *(const PG8_LAS bf16x8*)(lds + PG8_SB(b, h) + boff + n * 2048 + k * 1024); } while (0)
; #define PG8_MMA(ai, bj, At, Bt) do { __builtin_amdgcn_s_setprio(1); _Pragma("unroll") for (int m = 0; m < 4; ++m) _Pragma("unroll") for (int n = 0; n < 2; ++n) _Pragma("unroll") for (int k = 0; k < 2; ++k) \
;         acc[ai][bj][m][n] = __builtin_amdgcn_mfma_f32_16x16x32_bf16(Bt[n][k], At[m][k], acc[ai][bj][m][n], 0, 0, 0); __builtin_amdgcn_s_setprio(0); } while (0)
; #define PG8_WAIT_V(n) asm volatile("s_waitcnt vmcnt(" #n ")" ::: "memory")
; #define PG8_BAR __builtin_amdgcn_s_barrier()
; template <class Epi, class Sched, bool ALIGN_EPI = false, bool SP2 = false>
; __device__ __forceinline__ void gemm_phase(PG8_LAS unsigned char* lds, const Gemm g, const Sched& S, const Epi& E) {
;     ...
;         for (int t = 0; t < nt; t += 2) {
;             const bool last = (t == nt - 2);
;             const char* a1 = cA + (size_t)(t + 1) * kstep;
;             const char* a2 = last ? nA : cA + (size_t)(t + 2) * kstep; const char* b2 = last ? nB : cB + (size_t)(t + 2) * kstep;
;             const char* a3 = a2 + kstep; const char* b3 = b2 + kstep;
;             if (last && has_next) S.a_ready(nxt);
;             if constexpr (SP2) {
;             PG8_LDB(B0, 0, 0); PG8_LDB(B1, 0, 1); PG8_SCHED; PG8_LDA(At, 0, 0); PG8_STAGE(PG8_SA(1, 1), a1 + hstep, voffA);
;             PG8_WAIT_V(8); PG8_WAIT_L(0); PG8_BAR; PG8_MMA(0, 0, At, B0); PG8_MMA(0, 1, At, B1); PG8_BAR; PG8_SCHED;
;             PG8_LDA(At, 0, 1); PG8_STAGE(PG8_SB(0, 0), b2, voffB); PG8_STAGE(PG8_SB(0, 1), b2 + hstep, voffB); PG8_STAGE(PG8_SA(0, 0), a2, voffA);
;             PG8_WAIT_V(8); PG8_WAIT_L(0); PG8_BAR; PG8_MMA(1, 0, At, B0); PG8_MMA(1, 1, At, B1); PG8_BAR; PG8_SCHED;
.LBB0_1706:
	v_add_u32_e32 v162, s39, v152
	ds_read_b128 v[154:157], v162
	ds_read_b128 v[158:161], v162 offset:1024
	ds_read_b128 v[166:169], v162 offset:2048
	ds_read_b128 v[170:173], v162 offset:3072
	v_add_u32_e32 v162, s40, v152
	s_add_u32 s2, s14, s20
	ds_read_b128 v[174:177], v162
	ds_read_b128 v[178:181], v162 offset:1024
	ds_read_b128 v[182:185], v162 offset:2048
	ds_read_b128 v[186:189], v162 offset:3072
	s_addc_u32 s3, s15, s21
	s_add_u32 s2, s2, 0x100
	s_addc_u32 s3, s3, 0
	s_add_u32 s47, s44, s20
	s_addc_u32 s48, s45, s21
	s_cmpk_eq_i32 s20, 0x1500
	s_cselect_b32 s23, s19, s3
	s_cselect_b32 s22, s18, s2
	s_cselect_b32 s3, s7, s48
	s_cselect_b32 s2, s6, s47
	v_lshl_add_u64 v[162:163], v[146:147], 0, s[20:21]
	s_add_i32 m0, s30, 0xc000
	ds_read_b128 v[190:193], v153
	ds_read_b128 v[194:197], v153 offset:1024
	ds_read_b128 v[198:201], v153 offset:2048
	ds_read_b128 v[202:205], v153 offset:3072
	ds_read_b128 v[206:209], v153 offset:4096
	ds_read_b128 v[210:213], v153 offset:5120
	ds_read_b128 v[214:217], v153 offset:6144
	ds_read_b128 v[218:221], v153 offset:7168
	global_load_lds_dwordx4 v[162:163], off
	v_lshl_add_u64 v[162:163], v[148:149], 0, s[20:21]
	s_add_i32 m0, s30, 0xe000
	s_nop 0
	global_load_lds_dwordx4 v[162:163], off
	s_waitcnt vmcnt(8)
	s_waitcnt lgkmcnt(0)
	v_mfma_f32_16x16x32_bf16 v[70:73], v[154:157], v[190:193], v[70:73]
	v_mfma_f32_16x16x32_bf16 v[78:81], v[166:169], v[190:193], v[78:81]
	v_mfma_f32_16x16x32_bf16 v[94:97], v[154:157], v[198:201], v[94:97]
	v_mfma_f32_16x16x32_bf16 v[118:121], v[166:169], v[198:201], v[118:121]
	s_barrier
	s_setprio 1
	s_waitcnt lgkmcnt(0)
	v_mfma_f32_16x16x32_bf16 v[106:109], v[154:157], v[206:209], v[106:109]
	v_mfma_f32_16x16x32_bf16 v[114:117], v[166:169], v[206:209], v[114:117]
	v_mfma_f32_16x16x32_bf16 v[122:125], v[154:157], v[214:217], v[122:125]
	v_mfma_f32_16x16x32_bf16 v[126:129], v[166:169], v[214:217], v[126:129]
	v_mfma_f32_16x16x32_bf16 v[70:73], v[158:161], v[194:197], v[70:73]
	v_mfma_f32_16x16x32_bf16 v[78:81], v[170:173], v[194:197], v[78:81]
	v_mfma_f32_16x16x32_bf16 v[94:97], v[158:161], v[202:205], v[94:97]
	v_mfma_f32_16x16x32_bf16 v[118:121], v[170:173], v[202:205], v[118:121]
	v_mfma_f32_16x16x32_bf16 v[106:109], v[158:161], v[210:213], v[106:109]
	v_mfma_f32_16x16x32_bf16 v[114:117], v[170:173], v[210:213], v[114:117]
	v_mfma_f32_16x16x32_bf16 v[122:125], v[158:161], v[218:221], v[122:125]
	v_mfma_f32_16x16x32_bf16 v[126:129], v[170:173], v[218:221], v[126:129]
	s_setprio 0
	s_setprio 1
	v_mfma_f32_16x16x32_bf16 v[66:69], v[174:177], v[190:193], v[66:69]
	v_mfma_f32_16x16x32_bf16 v[74:77], v[182:185], v[190:193], v[74:77]
	v_mfma_f32_16x16x32_bf16 v[82:85], v[174:177], v[198:201], v[82:85]
	v_mfma_f32_16x16x32_bf16 v[86:89], v[182:185], v[198:201], v[86:89]
	v_mfma_f32_16x16x32_bf16 v[90:93], v[174:177], v[206:209], v[90:93]
	v_mfma_f32_16x16x32_bf16 v[98:101], v[182:185], v[206:209], v[98:101]
	v_mfma_f32_16x16x32_bf16 v[102:105], v[174:177], v[214:217], v[102:105]
	v_mfma_f32_16x16x32_bf16 v[110:113], v[182:185], v[214:217], v[110:113]
	v_mfma_f32_16x16x32_bf16 v[66:69], v[178:181], v[194:197], v[66:69]
	v_mfma_f32_16x16x32_bf16 v[74:77], v[186:189], v[194:197], v[74:77]
	v_mfma_f32_16x16x32_bf16 v[82:85], v[178:181], v[202:205], v[82:85]
	v_mfma_f32_16x16x32_bf16 v[86:89], v[186:189], v[202:205], v[86:89]
	v_mfma_f32_16x16x32_bf16 v[90:93], v[178:181], v[210:213], v[90:93]
	v_mfma_f32_16x16x32_bf16 v[98:101], v[186:189], v[210:213], v[98:101]
	v_mfma_f32_16x16x32_bf16 v[102:105], v[178:181], v[218:221], v[102:105]
	v_mfma_f32_16x16x32_bf16 v[110:113], v[186:189], v[218:221], v[110:113]
	s_setprio 0
	s_barrier
	s_add_i32 s47, s39, s29
	v_lshl_add_u64 v[162:163], s[2:3], 0, v[132:133]
	s_mov_b32 m0, s47
	ds_read_b128 v[190:193], v153 offset:16384
	ds_read_b128 v[194:197], v153 offset:17408
	ds_read_b128 v[198:201], v153 offset:18432
	ds_read_b128 v[202:205], v153 offset:19456
	ds_read_b128 v[206:209], v153 offset:20480
	ds_read_b128 v[210:213], v153 offset:21504
	ds_read_b128 v[214:217], v153 offset:22528
	ds_read_b128 v[218:221], v153 offset:23552
	global_load_lds_dwordx4 v[162:163], off
	s_add_i32 m0, s47, 0x2000
	s_add_u32 s48, s2, 0xb0000
	v_lshl_add_u64 v[222:223], s[2:3], 0, v[136:137]
	s_addc_u32 s49, s3, 0
	s_add_i32 s47, s40, s29
	global_load_lds_dwordx4 v[222:223], off
	v_lshl_add_u64 v[224:225], s[48:49], 0, v[132:133]
	s_mov_b32 m0, s47
	v_lshl_add_u64 v[226:227], s[22:23], 0, v[134:135]
	global_load_lds_dwordx4 v[224:225], off
	v_lshl_add_u64 v[224:225], s[48:49], 0, v[136:137]
	s_add_i32 m0, s47, 0x2000
	s_nop 0
	global_load_lds_dwordx4 v[224:225], off
	v_lshl_add_u64 v[224:225], s[22:23], 0, v[130:131]
	s_mov_b32 m0, s30
	s_nop 0
	global_load_lds_dwordx4 v[224:225], off
	s_mov_b32 m0, s31
	s_nop 0
	global_load_lds_dwordx4 v[226:227], off
	s_waitcnt vmcnt(8)
	s_waitcnt lgkmcnt(0)
	v_mfma_f32_16x16x32_bf16 v[62:65], v[154:157], v[190:193], v[62:65]
	v_mfma_f32_16x16x32_bf16 v[58:61], v[166:169], v[190:193], v[58:61]
	v_mfma_f32_16x16x32_bf16 v[46:49], v[154:157], v[198:201], v[46:49]
	v_mfma_f32_16x16x32_bf16 v[42:45], v[166:169], v[198:201], v[42:45]
	s_barrier
; #define PG8_STAGE(bufoff, gbase, voff) do { _Pragma("unroll") for (int _i = 0; _i < 2; ++_i) \
;         __builtin_amdgcn_global_load_lds((const unsigned*)((const char*)(gbase) + (voff)[_i]), (PG8_LAS unsigned*)(lds + (bufoff) + ldsw + _i * 8192), 16, 0, 0); } while (0)
; #define PG8_LDA(dst, b, h) do { _Pragma("unroll") for (int m = 0; m < 4; ++m) _Pragma("unroll") for (int k = 0; k < 2; ++k) dst[m][k] = *(const PG8_LAS bf16x8*)(lds + PG8_SA(b, h) + aoff + m * 2048 + k * 1024); } while (0)
; #define PG8_LDB(dst, b, h) do { _Pragma("unroll") for (int n = 0; n < 2; ++n) _Pragma("unroll") for (int k = 0; k < 2; ++k) dst[n][k] = *(const PG8_LAS bf16x8*)(lds + PG8_SB(b, h) + boff + n * 2048 + k * 1024); } while (0)
; #define PG8_MMA(ai, bj, At, Bt) do { __builtin_amdgcn_s_setprio(1); _Pragma("unroll") for (int m = 0; m < 4; ++m) _Pragma("unroll") for (int n = 0; n < 2; ++n) _Pragma("unroll") for (int k = 0; k < 2; ++k) \
;         acc[ai][bj][m][n] = __builtin_amdgcn_mfma_f32_16x16x32_bf16(Bt[n][k], At[m][k], acc[ai][bj][m][n], 0, 0, 0); __builtin_amdgcn_s_setprio(0); } while (0)
; #define PG8_WAIT_V(n) asm volatile("s_waitcnt vmcnt(" #n ")" ::: "memory")
; #define PG8_WAIT_L(n) asm volatile("s_waitcnt lgkmcnt(" #n ")" ::: "memory")
; #define PG8_BAR __builtin_amdgcn_s_barrier()
; #define PG8_SCHED __builtin_amdgcn_sched_barrier(0)
; template <class Epi, class Sched, bool ALIGN_EPI = false, bool SP2 = false>
; __device__ __forceinline__ void gemm_phase(PG8_LAS unsigned char* lds, const Gemm g, const Sched& S, const Epi& E) {
;     ...
;             PG8_WAIT_V(8); PG8_WAIT_L(0); PG8_BAR; PG8_MMA(1, 0, At, B0); PG8_MMA(1, 1, At, B1); PG8_BAR; PG8_SCHED;
;             PG8_LDB(B0, 1, 0); PG8_LDB(B1, 1, 1); PG8_SCHED; PG8_LDA(At, 1, 0); PG8_STAGE(PG8_SA(0, 1), a2 + hstep, voffA);
;             PG8_WAIT_V(8); PG8_WAIT_L(0); PG8_BAR; PG8_MMA(0, 0, At, B0); PG8_MMA(0, 1, At, B1); PG8_BAR; PG8_SCHED;
	s_setprio 1
	s_waitcnt lgkmcnt(0)
	v_mfma_f32_16x16x32_bf16 v[30:33], v[154:157], v[206:209], v[30:33]
	v_mfma_f32_16x16x32_bf16 v[26:29], v[166:169], v[206:209], v[26:29]
	v_mfma_f32_16x16x32_bf16 v[14:17], v[154:157], v[214:217], v[14:17]
	v_mfma_f32_16x16x32_bf16 v[10:13], v[166:169], v[214:217], v[10:13]
	v_mfma_f32_16x16x32_bf16 v[62:65], v[158:161], v[194:197], v[62:65]
	v_mfma_f32_16x16x32_bf16 v[58:61], v[170:173], v[194:197], v[58:61]
	v_mfma_f32_16x16x32_bf16 v[46:49], v[158:161], v[202:205], v[46:49]
	v_mfma_f32_16x16x32_bf16 v[42:45], v[170:173], v[202:205], v[42:45]
	v_mfma_f32_16x16x32_bf16 v[30:33], v[158:161], v[210:213], v[30:33]
	v_mfma_f32_16x16x32_bf16 v[26:29], v[170:173], v[210:213], v[26:29]
	v_mfma_f32_16x16x32_bf16 v[14:17], v[158:161], v[218:221], v[14:17]
	v_mfma_f32_16x16x32_bf16 v[10:13], v[170:173], v[218:221], v[10:13]
	s_setprio 0
	s_setprio 1
	v_mfma_f32_16x16x32_bf16 v[54:57], v[174:177], v[190:193], v[54:57]
	v_mfma_f32_16x16x32_bf16 v[50:53], v[182:185], v[190:193], v[50:53]
	v_mfma_f32_16x16x32_bf16 v[38:41], v[174:177], v[198:201], v[38:41]
	v_mfma_f32_16x16x32_bf16 v[34:37], v[182:185], v[198:201], v[34:37]
	v_mfma_f32_16x16x32_bf16 v[22:25], v[174:177], v[206:209], v[22:25]
	v_mfma_f32_16x16x32_bf16 v[18:21], v[182:185], v[206:209], v[18:21]
	v_mfma_f32_16x16x32_bf16 v[6:9], v[174:177], v[214:217], v[6:9]
	v_mfma_f32_16x16x32_bf16 v[2:5], v[182:185], v[214:217], v[2:5]
	v_mfma_f32_16x16x32_bf16 v[54:57], v[178:181], v[194:197], v[54:57]
	v_mfma_f32_16x16x32_bf16 v[50:53], v[186:189], v[194:197], v[50:53]
	v_mfma_f32_16x16x32_bf16 v[38:41], v[178:181], v[202:205], v[38:41]
	v_mfma_f32_16x16x32_bf16 v[34:37], v[186:189], v[202:205], v[34:37]
	v_mfma_f32_16x16x32_bf16 v[22:25], v[178:181], v[210:213], v[22:25]
	v_mfma_f32_16x16x32_bf16 v[18:21], v[186:189], v[210:213], v[18:21]
	v_mfma_f32_16x16x32_bf16 v[6:9], v[178:181], v[218:221], v[6:9]
	v_mfma_f32_16x16x32_bf16 v[2:5], v[186:189], v[218:221], v[2:5]
	s_setprio 0
	s_barrier
	s_add_i32 s47, 0, 0x18000
	v_add_u32_e32 v165, s47, v152
	s_add_i32 s48, 0, 0x1c000
	ds_read_b128 v[154:157], v165
	ds_read_b128 v[158:161], v165 offset:1024
	ds_read_b128 v[166:169], v165 offset:2048
	ds_read_b128 v[170:173], v165 offset:3072
	v_add_u32_e32 v165, s48, v152
	ds_read_b128 v[174:177], v165
	ds_read_b128 v[178:181], v165 offset:1024
	ds_read_b128 v[182:185], v165 offset:2048
	ds_read_b128 v[186:189], v165 offset:3072
	s_add_u32 s22, s22, 0xb0000
	s_addc_u32 s23, s23, 0
	s_mov_b32 m0, s33
	v_lshl_add_u64 v[228:229], s[22:23], 0, v[130:131]
	ds_read_b128 v[190:193], v153 offset:32768
	ds_read_b128 v[194:197], v153 offset:33792
	ds_read_b128 v[198:201], v153 offset:34816
	ds_read_b128 v[202:205], v153 offset:35840
	ds_read_b128 v[206:209], v153 offset:36864
	ds_read_b128 v[210:213], v153 offset:37888
	ds_read_b128 v[214:217], v153 offset:38912
	ds_read_b128 v[218:221], v153 offset:39936
	global_load_lds_dwordx4 v[228:229], off
	v_lshl_add_u64 v[228:229], s[22:23], 0, v[134:135]
	s_mov_b32 m0, s34
	s_nop 0
	global_load_lds_dwordx4 v[228:229], off
	s_waitcnt vmcnt(8)
	s_waitcnt lgkmcnt(0)
	v_mfma_f32_16x16x32_bf16 v[70:73], v[154:157], v[190:193], v[70:73]
	v_mfma_f32_16x16x32_bf16 v[78:81], v[166:169], v[190:193], v[78:81]
	v_mfma_f32_16x16x32_bf16 v[94:97], v[154:157], v[198:201], v[94:97]
	v_mfma_f32_16x16x32_bf16 v[118:121], v[166:169], v[198:201], v[118:121]
	s_barrier
	s_setprio 1
	s_waitcnt lgkmcnt(0)
	v_mfma_f32_16x16x32_bf16 v[106:109], v[154:157], v[206:209], v[106:109]
	v_mfma_f32_16x16x32_bf16 v[114:117], v[166:169], v[206:209], v[114:117]
	v_mfma_f32_16x16x32_bf16 v[122:125], v[154:157], v[214:217], v[122:125]
	v_mfma_f32_16x16x32_bf16 v[126:129], v[166:169], v[214:217], v[126:129]
	v_mfma_f32_16x16x32_bf16 v[70:73], v[158:161], v[194:197], v[70:73]
	v_mfma_f32_16x16x32_bf16 v[78:81], v[170:173], v[194:197], v[78:81]
	v_mfma_f32_16x16x32_bf16 v[94:97], v[158:161], v[202:205], v[94:97]
	v_mfma_f32_16x16x32_bf16 v[118:121], v[170:173], v[202:205], v[118:121]
	v_mfma_f32_16x16x32_bf16 v[106:109], v[158:161], v[210:213], v[106:109]
	v_mfma_f32_16x16x32_bf16 v[114:117], v[170:173], v[210:213], v[114:117]
	v_mfma_f32_16x16x32_bf16 v[122:125], v[158:161], v[218:221], v[122:125]
	v_mfma_f32_16x16x32_bf16 v[126:129], v[170:173], v[218:221], v[126:129]
	s_setprio 0
	s_setprio 1
	v_mfma_f32_16x16x32_bf16 v[66:69], v[174:177], v[190:193], v[66:69]
	v_mfma_f32_16x16x32_bf16 v[74:77], v[182:185], v[190:193], v[74:77]
	v_mfma_f32_16x16x32_bf16 v[82:85], v[174:177], v[198:201], v[82:85]
	v_mfma_f32_16x16x32_bf16 v[86:89], v[182:185], v[198:201], v[86:89]
	v_mfma_f32_16x16x32_bf16 v[90:93], v[174:177], v[206:209], v[90:93]
	v_mfma_f32_16x16x32_bf16 v[98:101], v[182:185], v[206:209], v[98:101]
	v_mfma_f32_16x16x32_bf16 v[102:105], v[174:177], v[214:217], v[102:105]
	v_mfma_f32_16x16x32_bf16 v[110:113], v[182:185], v[214:217], v[110:113]
	v_mfma_f32_16x16x32_bf16 v[66:69], v[178:181], v[194:197], v[66:69]
	v_mfma_f32_16x16x32_bf16 v[74:77], v[186:189], v[194:197], v[74:77]
	v_mfma_f32_16x16x32_bf16 v[82:85], v[178:181], v[202:205], v[82:85]
	v_mfma_f32_16x16x32_bf16 v[86:89], v[186:189], v[202:205], v[86:89]
	v_mfma_f32_16x16x32_bf16 v[90:93], v[178:181], v[210:213], v[90:93]
	v_mfma_f32_16x16x32_bf16 v[98:101], v[186:189], v[210:213], v[98:101]
	v_mfma_f32_16x16x32_bf16 v[102:105], v[178:181], v[218:221], v[102:105]
	v_mfma_f32_16x16x32_bf16 v[110:113], v[186:189], v[218:221], v[110:113]
	s_setprio 0
	s_barrier
; #define PG8_STAGE(bufoff, gbase, voff) do { _Pragma("unroll") for (int _i = 0; _i < 2; ++_i) \
;         __builtin_amdgcn_global_load_lds((const unsigned*)((const char*)(gbase) + (voff)[_i]), (PG8_LAS unsigned*)(lds + (bufoff) + ldsw + _i * 8192), 16, 0, 0); } while (0)
; #define PG8_LDA(dst, b, h) do { _Pragma("unroll") for (int m = 0; m < 4; ++m) _Pragma("unroll") for (int k = 0; k < 2; ++k) dst[m][k] = *(const PG8_LAS bf16x8*)(lds + PG8_SA(b, h) + aoff + m * 2048 + k * 1024); } while (0)
; #define PG8_MMA(ai, bj, At, Bt) do { __builtin_amdgcn_s_setprio(1); _Pragma("unroll") for (int m = 0; m < 4; ++m) _Pragma("unroll") for (int n = 0; n < 2; ++n) _Pragma("unroll") for (int k = 0; k < 2; ++k) \
;         acc[ai][bj][m][n] = __builtin_amdgcn_mfma_f32_16x16x32_bf16(Bt[n][k], At[m][k], acc[ai][bj][m][n], 0, 0, 0); __builtin_amdgcn_s_setprio(0); } while (0)
; #define PG8_WAIT_V(n) asm volatile("s_waitcnt vmcnt(" #n ")" ::: "memory")
; #define PG8_WAIT_L(n) asm volatile("s_waitcnt lgkmcnt(" #n ")" ::: "memory")
; #define PG8_BAR __builtin_amdgcn_s_barrier()
; #define PG8_SCHED __builtin_amdgcn_sched_barrier(0)
; template <class Epi, class Sched, bool ALIGN_EPI = false, bool SP2 = false>
; __device__ __forceinline__ void gemm_phase(PG8_LAS unsigned char* lds, const Gemm g, const Sched& S, const Epi& E) {
;     ...
;             PG8_LDA(At, 1, 1); PG8_STAGE(PG8_SB(1, 0), b3, voffB); PG8_STAGE(PG8_SB(1, 1), b3 + hstep, voffB); PG8_STAGE(PG8_SA(1, 0), a3, voffA);
;             PG8_WAIT_V(8); PG8_WAIT_L(0); PG8_BAR; PG8_MMA(1, 0, At, B0); PG8_MMA(1, 1, At, B1); PG8_BAR; PG8_SCHED;
;     ...
;         if (!has_next) break;
; #pragma unroll
;         for (int a = 0; a < 2; ++a)
; #pragma unroll
;             for (int b = 0; b < 2; ++b)
; #pragma unroll
;                 for (int m = 0; m < 4; ++m)
; #pragma unroll
;                     for (int n = 0; n < 2; ++n) acc[a][b][m][n] = (f32x4){0.f, 0.f, 0.f, 0.f};
	s_add_i32 s22, s47, s29
	v_lshl_add_u64 v[162:163], v[162:163], 0, s[16:17]
	s_mov_b32 m0, s22
	ds_read_b128 v[190:193], v153 offset:49152
	ds_read_b128 v[194:197], v153 offset:50176
	ds_read_b128 v[198:201], v153 offset:51200
	ds_read_b128 v[202:205], v153 offset:52224
	ds_read_b128 v[206:209], v153 offset:53248
	ds_read_b128 v[210:213], v153 offset:54272
	ds_read_b128 v[214:217], v153 offset:55296
	ds_read_b128 v[218:221], v153 offset:56320
	global_load_lds_dwordx4 v[162:163], off
	s_add_i32 m0, s22, 0x2000
	s_add_u32 s2, s2, 0xb0080
	v_lshl_add_u64 v[162:163], v[222:223], 0, s[16:17]
	s_addc_u32 s3, s3, 0
	s_add_i32 s22, s48, s29
	global_load_lds_dwordx4 v[162:163], off
	v_lshl_add_u64 v[162:163], s[2:3], 0, v[132:133]
	s_mov_b32 m0, s22
	s_nop 0
	global_load_lds_dwordx4 v[162:163], off
	v_lshl_add_u64 v[162:163], s[2:3], 0, v[136:137]
	s_add_i32 m0, s22, 0x2000
	s_nop 0
	global_load_lds_dwordx4 v[162:163], off
	v_lshl_add_u64 v[162:163], v[224:225], 0, s[16:17]
	s_mov_b32 m0, s37
	s_nop 0
	global_load_lds_dwordx4 v[162:163], off
	v_lshl_add_u64 v[162:163], v[226:227], 0, s[16:17]
	s_mov_b32 m0, s38
	s_nop 0
	global_load_lds_dwordx4 v[162:163], off
	s_waitcnt vmcnt(8)
	s_waitcnt lgkmcnt(0)
	v_mfma_f32_16x16x32_bf16 v[62:65], v[154:157], v[190:193], v[62:65]
	v_mfma_f32_16x16x32_bf16 v[58:61], v[166:169], v[190:193], v[58:61]
	v_mfma_f32_16x16x32_bf16 v[46:49], v[154:157], v[198:201], v[46:49]
	v_mfma_f32_16x16x32_bf16 v[42:45], v[166:169], v[198:201], v[42:45]
	s_barrier
	s_setprio 1
	s_waitcnt lgkmcnt(0)
	v_mfma_f32_16x16x32_bf16 v[30:33], v[154:157], v[206:209], v[30:33]
	v_mfma_f32_16x16x32_bf16 v[26:29], v[166:169], v[206:209], v[26:29]
	v_mfma_f32_16x16x32_bf16 v[14:17], v[154:157], v[214:217], v[14:17]
	v_mfma_f32_16x16x32_bf16 v[10:13], v[166:169], v[214:217], v[10:13]
	v_mfma_f32_16x16x32_bf16 v[62:65], v[158:161], v[194:197], v[62:65]
	v_mfma_f32_16x16x32_bf16 v[58:61], v[170:173], v[194:197], v[58:61]
	v_mfma_f32_16x16x32_bf16 v[46:49], v[158:161], v[202:205], v[46:49]
	v_mfma_f32_16x16x32_bf16 v[42:45], v[170:173], v[202:205], v[42:45]
	v_mfma_f32_16x16x32_bf16 v[30:33], v[158:161], v[210:213], v[30:33]
	v_mfma_f32_16x16x32_bf16 v[26:29], v[170:173], v[210:213], v[26:29]
	v_mfma_f32_16x16x32_bf16 v[14:17], v[158:161], v[218:221], v[14:17]
	v_mfma_f32_16x16x32_bf16 v[10:13], v[170:173], v[218:221], v[10:13]
	s_setprio 0
	s_setprio 1
	v_mfma_f32_16x16x32_bf16 v[54:57], v[174:177], v[190:193], v[54:57]
	v_mfma_f32_16x16x32_bf16 v[50:53], v[182:185], v[190:193], v[50:53]
	v_mfma_f32_16x16x32_bf16 v[38:41], v[174:177], v[198:201], v[38:41]
	v_mfma_f32_16x16x32_bf16 v[34:37], v[182:185], v[198:201], v[34:37]
	v_mfma_f32_16x16x32_bf16 v[22:25], v[174:177], v[206:209], v[22:25]
	v_mfma_f32_16x16x32_bf16 v[18:21], v[182:185], v[206:209], v[18:21]
	v_mfma_f32_16x16x32_bf16 v[6:9], v[174:177], v[214:217], v[6:9]
	v_mfma_f32_16x16x32_bf16 v[2:5], v[182:185], v[214:217], v[2:5]
	v_mfma_f32_16x16x32_bf16 v[54:57], v[178:181], v[194:197], v[54:57]
	v_mfma_f32_16x16x32_bf16 v[50:53], v[186:189], v[194:197], v[50:53]
	v_mfma_f32_16x16x32_bf16 v[38:41], v[178:181], v[202:205], v[38:41]
	v_mfma_f32_16x16x32_bf16 v[34:37], v[186:189], v[202:205], v[34:37]
	v_mfma_f32_16x16x32_bf16 v[22:25], v[178:181], v[210:213], v[22:25]
	v_mfma_f32_16x16x32_bf16 v[18:21], v[186:189], v[210:213], v[18:21]
	v_mfma_f32_16x16x32_bf16 v[6:9], v[178:181], v[218:221], v[6:9]
	v_mfma_f32_16x16x32_bf16 v[2:5], v[186:189], v[218:221], v[2:5]
	s_setprio 0
	s_barrier
	s_add_i32 s46, s46, 2
	s_add_u32 s20, s20, 0x100
	s_addc_u32 s21, s21, 0
	s_cmp_gt_u32 s46, 41
	s_cbranch_scc0 .LBB0_1706
	s_add_u32 s2, s44, 0xffffff00
	s_addc_u32 s3, s45, -1
	s_and_b64 vcc, exec, s[4:5]
	s_cbranch_vccnz .LBB0_1709
	v_mov_b32_e32 v2, 0
	s_mov_b32 s12, s41
	s_mov_b32 s25, s42
	s_mov_b64 s[14:15], s[18:19]
	s_mov_b32 s36, s43
	v_mov_b32_e32 v3, v2
	v_mov_b64_e32 v[4:5], v[2:3]
	v_mov_b64_e32 v[6:7], v[2:3]
	v_mov_b64_e32 v[8:9], v[2:3]
	v_mov_b64_e32 v[18:19], v[2:3]
	v_mov_b64_e32 v[20:21], v[2:3]
	v_mov_b64_e32 v[22:23], v[2:3]
	v_mov_b64_e32 v[24:25], v[2:3]
	v_mov_b64_e32 v[34:35], v[2:3]
	v_mov_b64_e32 v[36:37], v[2:3]
	v_mov_b64_e32 v[38:39], v[2:3]
	v_mov_b64_e32 v[40:41], v[2:3]
	v_mov_b64_e32 v[50:51], v[2:3]
	v_mov_b64_e32 v[52:53], v[2:3]
	v_mov_b64_e32 v[54:55], v[2:3]
	v_mov_b64_e32 v[56:57], v[2:3]
	v_mov_b64_e32 v[10:11], v[2:3]
	v_mov_b64_e32 v[12:13], v[2:3]
	v_mov_b64_e32 v[14:15], v[2:3]
	v_mov_b64_e32 v[16:17], v[2:3]
	v_mov_b64_e32 v[26:27], v[2:3]
	v_mov_b64_e32 v[28:29], v[2:3]
	v_mov_b64_e32 v[30:31], v[2:3]
	v_mov_b64_e32 v[32:33], v[2:3]
	v_mov_b64_e32 v[42:43], v[2:3]
	v_mov_b64_e32 v[44:45], v[2:3]
	v_mov_b64_e32 v[46:47], v[2:3]
	v_mov_b64_e32 v[48:49], v[2:3]
	v_mov_b64_e32 v[58:59], v[2:3]
	v_mov_b64_e32 v[60:61], v[2:3]
	v_mov_b64_e32 v[62:63], v[2:3]
	v_mov_b64_e32 v[64:65], v[2:3]
	v_mov_b64_e32 v[110:111], v[2:3]
	v_mov_b64_e32 v[112:113], v[2:3]
	v_mov_b64_e32 v[102:103], v[2:3]
	v_mov_b64_e32 v[104:105], v[2:3]
	v_mov_b64_e32 v[98:99], v[2:3]
	v_mov_b64_e32 v[100:101], v[2:3]
	v_mov_b64_e32 v[90:91], v[2:3]
	v_mov_b64_e32 v[92:93], v[2:3]
	v_mov_b64_e32 v[86:87], v[2:3]
	v_mov_b64_e32 v[88:89], v[2:3]
	v_mov_b64_e32 v[82:83], v[2:3]
	v_mov_b64_e32 v[84:85], v[2:3]
	v_mov_b64_e32 v[74:75], v[2:3]
	v_mov_b64_e32 v[76:77], v[2:3]
	v_mov_b64_e32 v[66:67], v[2:3]
	v_mov_b64_e32 v[68:69], v[2:3]
	v_mov_b64_e32 v[126:127], v[2:3]
	v_mov_b64_e32 v[128:129], v[2:3]
	v_mov_b64_e32 v[122:123], v[2:3]
	v_mov_b64_e32 v[124:125], v[2:3]
	v_mov_b64_e32 v[114:115], v[2:3]
	v_mov_b64_e32 v[116:117], v[2:3]
	v_mov_b64_e32 v[106:107], v[2:3]
	v_mov_b64_e32 v[108:109], v[2:3]
	v_mov_b64_e32 v[118:119], v[2:3]
	v_mov_b64_e32 v[120:121], v[2:3]
	v_mov_b64_e32 v[94:95], v[2:3]
	v_mov_b64_e32 v[96:97], v[2:3]
	v_mov_b64_e32 v[78:79], v[2:3]
	v_mov_b64_e32 v[80:81], v[2:3]
	v_mov_b64_e32 v[70:71], v[2:3]
	v_mov_b64_e32 v[72:73], v[2:3]
	s_andn2_b64 vcc, exec, s[0:1]
	s_cbranch_vccnz .LBB0_1710
	s_branch .LBB0_1711
